# strategy 7: phase B loop-invariant bpermute lane addresses hoisted out of the chunk loop; fast chunk path row sum without the 0+ add
# baseline (speedup 1.0000x reference)
; DI int my_tid() { int t = threadIdx.x; asm volatile("" : "+v"(t)); return t; }
; DI void sb_attn_wave(const Params& p, int b, int h, int t0, bf16_t* ybase) {
;   const int lane = my_tid() & 63, qi = lane & 15, quad = lane >> 4;
;   const bf16_t* Q = p.sbq() + (long)(b * 8 + h) * SEQ * 64;
;   const bf16_t* K = p.sbk() + (long)(b * 8 + h) * SEQ * 64;
;   const bf16_t* Vt = p.sbvt() + (long)(b * 8 + h) * 64 * SEQ;
;   const int tA = t0 + qi, tB = t0 + 16 + qi;
;   bf16x8 qa[2], qb[2];
;   qa[0] = ld8(Q + (long)tA * 64 + quad * 8); qa[1] = ld8(Q + (long)tA * 64 + 32 + quad * 8);
;   qb[0] = ld8(Q + (long)tB * 64 + quad * 8); qb[1] = ld8(Q + (long)tB * 64 + 32 + quad * 8);
;   f32x4 oa[4], ob[4];
; #pragma unroll
;   for (int dt = 0; dt < 4; ++dt) { oa[dt] = (f32x4){0.f, 0.f, 0.f, 0.f}; ob[dt] = oa[dt]; }
;   float ca = 0.f, cb = 0.f;
;   const int krow = 8 * (qi >> 2) + (qi & 3);
;   const bf16_t* kp0 = K + (long)krow * 64 + quad * 8;
;   const bf16_t* vp0 = Vt + qi * 32 + 8 * quad;
;   int kb = t0;
;   SbFrag f0, f1, f2;
;   sb_load(f0, kp0, vp0, kb); sb_load(f1, kp0, vp0, max(kb - 32, 0));
.LBB0_551:
	s_mov_b64 s[4:5], 0
	s_add_u32 s18, s92, s4
	s_addc_u32 s19, s93, s5
	s_cmpk_gt_i32 s17, 0x7f
	s_mov_b64 s[4:5], -1
	s_cbranch_scc0 .LBB0_571
	v_mov_b32_e32 v0, v210
	s_lshl_b32 s4, s17, 1
	v_ashrrev_i32_e32 v0, 1, v0
	s_and_b32 s4, s4, 0x7fffff00
	v_and_b32_e32 v6, 0xffffffe0, v0
	v_subrev_u32_e32 v7, s4, v6
	s_and_b32 s4, s17, 0x7f
	s_and_b32 s10, s16, 0x7fffff00
	v_mov_b32_e32 v8, v210
	s_lshl_b32 s4, s4, 18
	s_waitcnt vmcnt(5)
	v_add_u32_e32 v154, 0x800, v7
	s_add_u32 s4, s18, s4
	v_and_b32_e32 v4, 15, v8
	s_addc_u32 s5, s19, 0
	v_or_b32_e32 v156, v154, v4
	s_add_u32 s8, s4, 0x6170000
	v_ashrrev_i32_e32 v157, 31, v156
	v_bfe_u32 v164, v8, 4, 2
	s_addc_u32 s9, s5, 0
	v_lshlrev_b64 v[2:3], 7, v[156:157]
	v_or_b32_e32 v152, 16, v156
	v_lshl_add_u64 v[2:3], s[8:9], 0, v[2:3]
	v_lshlrev_b32_e32 v0, 4, v164
	v_lshl_add_u64 v[2:3], v[2:3], 0, v[0:1]
	v_ashrrev_i32_e32 v153, 31, v152
	global_load_dwordx4 v[28:31], v[2:3], off
	global_load_dwordx4 v[32:35], v[2:3], off offset:64
	v_lshlrev_b64 v[2:3], 7, v[152:153]
	v_lshl_add_u64 v[2:3], s[8:9], 0, v[2:3]
	v_lshl_add_u64 v[2:3], v[2:3], 0, v[0:1]
	global_load_dwordx4 v[36:39], v[2:3], off
	global_load_dwordx4 v[40:43], v[2:3], off offset:64
	v_lshlrev_b32_e32 v2, 1, v8
	v_and_b32_e32 v3, 3, v8
	v_and_or_b32 v2, v2, 24, v3
	v_lshlrev_b32_e32 v2, 7, v2
	v_mov_b32_e32 v3, v1
	v_lshl_add_u64 v[2:3], s[4:5], 0, v[2:3]
	v_lshl_add_u64 v[2:3], v[2:3], 0, v[0:1]
	s_mov_b64 s[8:9], 0x8170000
	s_waitcnt vmcnt(8)
	v_lshl_add_u64 v[158:159], v[2:3], 0, s[8:9]
	v_lshlrev_b32_e32 v2, 6, v4
	v_mov_b32_e32 v3, v1
	v_lshl_add_u64 v[2:3], s[4:5], 0, v[2:3]
	v_lshl_add_u64 v[2:3], v[2:3], 0, v[0:1]
	s_mov_b64 s[4:5], 0xa170000
	v_ashrrev_i32_e32 v155, 31, v154
	v_lshl_add_u64 v[160:161], v[2:3], 0, s[4:5]
	v_lshlrev_b64 v[2:3], 7, v[154:155]
	v_lshl_add_u64 v[4:5], v[158:159], 0, v[2:3]
	global_load_dwordx4 v[108:111], v[4:5], off
	global_load_dwordx4 v[104:107], v[4:5], off offset:64
	v_add_u32_e32 v4, 0x804, v7
	v_ashrrev_i32_e32 v5, 31, v4
	v_lshlrev_b64 v[4:5], 7, v[4:5]
	v_max_i32_e32 v9, 32, v154
	v_lshl_add_u64 v[4:5], v[158:159], 0, v[4:5]
	v_lshl_add_u64 v[2:3], v[160:161], 0, v[2:3]
	v_subrev_u32_e32 v0, 32, v9
	global_load_dwordx4 v[112:115], v[4:5], off
	global_load_dwordx4 v[100:103], v[4:5], off offset:64
	global_load_dwordx4 v[68:71], v[2:3], off
	global_load_dwordx4 v[72:75], v[2:3], off offset:1024
	global_load_dwordx4 v[60:63], v[2:3], off offset:2048
	global_load_dwordx4 v[52:55], v[2:3], off offset:3072
	v_lshlrev_b64 v[2:3], 7, v[0:1]
	v_lshl_add_u64 v[4:5], v[158:159], 0, v[2:3]
	v_subrev_u32_e32 v0, 28, v9
	global_load_dwordx4 v[120:123], v[4:5], off
	global_load_dwordx4 v[116:119], v[4:5], off offset:64
	v_lshlrev_b64 v[4:5], 7, v[0:1]
	v_lshl_add_u64 v[4:5], v[158:159], 0, v[4:5]
	v_lshl_add_u64 v[2:3], v[160:161], 0, v[2:3]
	global_load_dwordx4 v[128:131], v[4:5], off
	global_load_dwordx4 v[124:127], v[4:5], off offset:64
	global_load_dwordx4 v[80:83], v[2:3], off
	global_load_dwordx4 v[76:79], v[2:3], off offset:1024
	global_load_dwordx4 v[64:67], v[2:3], off offset:2048
	global_load_dwordx4 v[56:59], v[2:3], off offset:3072
	v_lshrrev_b32_e32 v0, 4, v8
	v_bitop3_b32 v2, v0, 1, 3 bitop3:0x6c
	v_cmp_gt_u32_e32 vcc, v2, v164
	v_bitop3_b32 v2, v0, 2, 3 bitop3:0x6c
	v_bitop3_b32 v0, v0, 3, v0 bitop3:0xc
	v_cmp_gt_u32_e64 s[44:45], v2, v164
	v_cmp_gt_u32_e64 s[46:47], v0, v164
	v_subrev_u32_e32 v0, s10, v6
	v_mov_b32_e32 v2, v1
	v_mov_b32_e32 v3, v1
	v_add_u32_e32 v165, 0x7e0, v7
	v_add_u32_e32 v166, 0x7a0, v0
	v_mov_b32_e32 v0, v1
	v_mov_b32_e32 v162, 0
	v_mov_b64_e32 v[6:7], v[2:3]
	v_mov_b64_e32 v[10:11], v[2:3]
	v_mov_b64_e32 v[14:15], v[2:3]
	s_waitcnt vmcnt(20)
	v_mov_b64_e32 v[22:23], v[2:3]
	v_mov_b64_e32 v[26:27], v[2:3]
	v_mov_b64_e32 v[46:47], v[2:3]
	v_mov_b64_e32 v[18:19], v[2:3]
	v_mov_b64_e32 v[50:51], v[2:3]
	v_lshlrev_b32_e32 v155, 3, v164
	s_mov_b64 s[4:5], 0
	v_mov_b64_e32 v[4:5], v[0:1]
	v_mov_b64_e32 v[8:9], v[0:1]
	v_mov_b64_e32 v[12:13], v[0:1]
	v_mov_b64_e32 v[20:21], v[0:1]
	v_mov_b64_e32 v[24:25], v[0:1]
	v_mov_b64_e32 v[44:45], v[0:1]
	v_mov_b64_e32 v[16:17], v[0:1]
	v_mov_b64_e32 v[48:49], v[0:1]
	v_mov_b32_e32 v163, v162
	v_xor_b32_e32 v250, 16, v228
	v_lshlrev_b32_e32 v250, 2, v250
	v_xor_b32_e32 v251, 32, v228
	v_lshlrev_b32_e32 v251, 2, v251
	s_branch .LBB0_556

; #define MFMA16(a, b, c) __builtin_amdgcn_mfma_f32_16x16x32_bf16((a), (b), (c), 0, 0, 0)
; DI unsigned pk2(float lo, float hi) { f32x2 v = {lo, hi}; bf16x2_t b = __builtin_convertvector(v, bf16x2_t); return __builtin_bit_cast(unsigned, b); }
; #define SB_STEP(F, KB) (((KB) + 32 <= t0) ? (sb_chunk<true>(F, KB, tA, quad, qa, oa, ca), sb_chunk<true>(F, KB, tB, quad, qb, ob, cb)) : (sb_chunk<false>(F, KB, tA, quad, qa, oa, ca), sb_chunk<false>(F, KB, tB, quad, qb, ob, cb)), __all(ca < -160.f && cb < -160.f))
; template <bool FULL>
; DI void sb_chunk(const SbFrag& f, int kb, int t, int quad, const bf16x8 (&qf)[2], f32x4 (&o)[4], float& carry) {
;   f32x4 s[2];
; #pragma unroll
;   for (int a = 0; a < 2; ++a) {
;     s[a] = MFMA16(f.k[a][0], qf[0], ((f32x4){0.f, 0.f, 0.f, 0.f}));
;     s[a] = MFMA16(f.k[a][1], qf[1], s[a]);
;   }
;   float beta[8], om[8];
;   float prod = 1.f;
; #pragma unroll
;   for (int idx = 0; idx < 8; ++idx) {
;     const float z2 = fminf(s[idx >> 2][idx & 3] * (0.125f * 1.44269504089f), 60.f);
;     const float e = __builtin_amdgcn_exp2f(z2);
;     const float r = __builtin_amdgcn_rcpf(1.f + e);
;     const bool val = FULL ? true : (kb + 8 * quad + idx < t);
;     om[idx] = val ? r : 1.f;
;     beta[idx] = val ? e * r : 0.f;
;     prod *= om[idx];
;   }
;   const float a1 = __shfl_xor(prod, 16), a2 = __shfl_xor(prod, 32), a3 = __shfl_xor(a1, 32);
;   const float higher = ((quad ^ 1) > quad ? a1 : 1.f) * ((quad ^ 2) > quad ? a2 : 1.f) * ((quad ^ 3) > quad ? a3 : 1.f);
;   float q = __builtin_amdgcn_exp2f(carry) * higher;
;   float wv[8];
; #pragma unroll
;     ...
;   carry += __builtin_amdgcn_logf((prod * a1) * (a2 * a3));
;   const bf16x8 pf = mk8((u32x4){pk2(wv[0], wv[1]), pk2(wv[2], wv[3]), pk2(wv[4], wv[5]), pk2(wv[6], wv[7])});
; #pragma unroll
;   for (int dt = 0; dt < 4; ++dt) o[dt] = MFMA16(f.v[dt], pf, o[dt]);
; }
; DI void sb_attn_wave(const Params& p, int b, int h, int t0, bf16_t* ybase) {
;     ...
;   while (true) {
;     sb_load(f2, kp0, vp0, max(kb - 64, 0));
;     if (SB_STEP(f0, kb) || kb < 32) break;
.LBB0_556:
	v_add_u32_e32 v0, 32, v166
	v_max_i32_e32 v0, 0, v0
	v_lshlrev_b64 v[2:3], 7, v[0:1]
	s_waitcnt vmcnt(0)
	v_lshl_add_u64 v[84:85], v[158:159], 0, v[2:3]
	v_or_b32_e32 v0, 4, v0
	global_load_dwordx4 v[136:139], v[84:85], off
	global_load_dwordx4 v[140:143], v[84:85], off offset:64
	v_lshlrev_b64 v[84:85], 7, v[0:1]
	v_lshl_add_u64 v[84:85], v[158:159], 0, v[84:85]
	v_lshl_add_u64 v[2:3], v[160:161], 0, v[2:3]
	global_load_dwordx4 v[144:147], v[84:85], off
	global_load_dwordx4 v[132:135], v[84:85], off offset:64
	global_load_dwordx4 v[92:95], v[2:3], off
	global_load_dwordx4 v[96:99], v[2:3], off offset:1024
	global_load_dwordx4 v[88:91], v[2:3], off offset:2048
	s_nop 0
	global_load_dwordx4 v[84:87], v[2:3], off offset:3072
	v_exp_f32_e32 v168, v163
	v_exp_f32_e32 v0, v162
	v_add_u32_e32 v167, 0x60, v166
	v_cmp_le_i32_e64 s[8:9], v167, v165
	s_and_saveexec_b64 s[10:11], s[8:9]
	s_xor_b64 s[10:11], exec, s[10:11]
	s_cbranch_execz .LBB0_558
	s_waitcnt vmcnt(23)
	v_mfma_f32_16x16x32_bf16 v[148:151], v[108:111], v[28:31], 0
	s_waitcnt vmcnt(22)
	v_mfma_f32_16x16x32_bf16 v[148:151], v[104:107], v[32:35], v[148:151]
	s_waitcnt vmcnt(21)
	v_mfma_f32_16x16x32_bf16 v[170:173], v[112:115], v[28:31], 0
	s_waitcnt vmcnt(20)
	v_mfma_f32_16x16x32_bf16 v[170:173], v[100:103], v[32:35], v[170:173]
	s_nop 3
	v_mul_f32_e32 v2, 0x3e38aa3b, v148
	v_min_f32_e32 v2, 0x42700000, v2
	v_exp_f32_e32 v2, v2
	v_mul_f32_e32 v3, 0x3e38aa3b, v149
	v_mul_f32_e32 v148, 0x3e38aa3b, v150
	v_min_f32_e32 v3, 0x42700000, v3
	v_add_f32_e32 v149, 1.0, v2
	v_exp_f32_e32 v3, v3
	v_min_f32_e32 v148, 0x42700000, v148
	v_rcp_f32_e32 v150, v149
	v_mul_f32_e32 v149, 0x3e38aa3b, v151
	v_exp_f32_e32 v148, v148
	v_min_f32_e32 v149, 0x42700000, v149
	v_mul_f32_e32 v170, 0x3e38aa3b, v170
	v_exp_f32_e32 v149, v149
	v_min_f32_e32 v170, 0x42700000, v170
	v_mul_f32_e32 v171, 0x3e38aa3b, v171
	v_exp_f32_e32 v170, v170
	v_min_f32_e32 v171, 0x42700000, v171
	v_mul_f32_e32 v172, 0x3e38aa3b, v172
	v_add_f32_e32 v169, 1.0, v3
	v_exp_f32_e32 v171, v171
	v_min_f32_e32 v172, 0x42700000, v172
	v_mul_f32_e32 v173, 0x3e38aa3b, v173
	v_rcp_f32_e32 v151, v169
	v_add_f32_e32 v169, 1.0, v148
	v_exp_f32_e32 v172, v172
	v_min_f32_e32 v173, 0x42700000, v173
	v_rcp_f32_e32 v174, v169
	v_add_f32_e32 v169, 1.0, v149
	v_exp_f32_e32 v173, v173
	v_rcp_f32_e32 v175, v169
	v_add_f32_e32 v169, 1.0, v170
	v_rcp_f32_e32 v176, v169
	v_add_f32_e32 v169, 1.0, v171
	v_rcp_f32_e32 v177, v169
	v_add_f32_e32 v169, 1.0, v172
	v_rcp_f32_e32 v178, v169
	v_add_f32_e32 v169, 1.0, v173
	v_rcp_f32_e32 v179, v169
	v_pk_mul_f32 v[2:3], v[2:3], v[150:151]
	v_mfma_f32_16x16x32_bf16 v[108:111], v[108:111], v[36:39], 0
	v_pk_mul_f32 v[172:173], v[172:173], v[178:179]
	v_pk_mul_f32 v[170:171], v[170:171], v[176:177]
	v_mul_f32_e32 v169, v150, v151
	v_mul_f32_e32 v169, v174, v169
	v_mul_f32_e32 v169, v175, v169
	v_mul_f32_e32 v169, v176, v169
	v_mul_f32_e32 v169, v177, v169
	v_mul_f32_e32 v169, v178, v169
	v_mul_f32_e32 v181, v179, v169
	ds_bpermute_b32 v183, v250, v181
	ds_bpermute_b32 v180, v251, v181
	v_mfma_f32_16x16x32_bf16 v[104:107], v[104:107], v[40:43], v[108:111]
	v_mul_f32_e64 v148, v148, v174
	v_mul_f32_e64 v149, v149, v175
	s_waitcnt lgkmcnt(1)
	ds_bpermute_b32 v182, v251, v183
	s_waitcnt lgkmcnt(1)
	v_cndmask_b32_e64 v150, 1.0, v180, s[44:45]
	v_cndmask_b32_e32 v169, 1.0, v183, vcc
	v_mul_f32_e32 v150, v169, v150
	v_mfma_f32_16x16x32_bf16 v[108:111], v[112:115], v[36:39], 0
	s_waitcnt lgkmcnt(0)
	v_cndmask_b32_e64 v169, 1.0, v182, s[46:47]
	v_mul_f32_e32 v150, v150, v169
	v_mul_f32_e32 v169, v168, v150
	v_mul_f32_e32 v168, v179, v169
	v_pk_mul_f32 v[172:173], v[172:173], v[168:169]
	v_mul_f32_e32 v169, v178, v168
	v_mul_f32_e32 v168, v177, v169
	v_pk_mul_f32 v[170:171], v[170:171], v[168:169]
	v_mul_f32_e32 v169, v176, v168
	v_mul_f32_e32 v168, v175, v169
	v_pk_mul_f32 v[176:177], v[148:149], v[168:169]
	v_mul_f32_e32 v149, v174, v168
	v_mul_f32_e32 v148, v151, v149
	v_pk_mul_f32 v[2:3], v[2:3], v[148:149]
	v_mfma_f32_16x16x32_bf16 v[100:103], v[100:103], v[40:43], v[108:111]
	v_cvt_pk_bf16_f32 v148, v2, v3
	v_mul_f32_e32 v2, 0x3e38aa3b, v104
	v_mul_f32_e32 v3, 0x3e38aa3b, v105
	v_min_f32_e32 v2, 0x42700000, v2
	v_min_f32_e32 v3, 0x42700000, v3
	v_mul_f32_e32 v106, 0x3e38aa3b, v106
	v_exp_f32_e32 v2, v2
	v_exp_f32_e32 v3, v3
	v_min_f32_e32 v106, 0x42700000, v106
	v_mul_f32_e32 v107, 0x3e38aa3b, v107
	v_exp_f32_e32 v106, v106
	v_min_f32_e32 v107, 0x42700000, v107
	v_mul_f32_e32 v100, 0x3e38aa3b, v100
	v_exp_f32_e32 v107, v107
	v_min_f32_e32 v100, 0x42700000, v100
	v_mul_f32_e32 v101, 0x3e38aa3b, v101
	v_exp_f32_e32 v100, v100
	v_min_f32_e32 v101, 0x42700000, v101
	v_mul_f32_e32 v102, 0x3e38aa3b, v102
	v_add_f32_e32 v104, 1.0, v2
	v_add_f32_e32 v105, 1.0, v3
	v_exp_f32_e32 v101, v101
	v_min_f32_e32 v102, 0x42700000, v102
	v_mul_f32_e32 v103, 0x3e38aa3b, v103
	v_rcp_f32_e32 v104, v104
	v_rcp_f32_e32 v105, v105
	v_add_f32_e32 v108, 1.0, v106
	v_exp_f32_e32 v102, v102
	v_min_f32_e32 v103, 0x42700000, v103
	v_rcp_f32_e32 v108, v108
	v_add_f32_e32 v109, 1.0, v107
	v_exp_f32_e32 v103, v103
	v_rcp_f32_e32 v109, v109
	v_add_f32_e32 v110, 1.0, v100
	v_rcp_f32_e32 v110, v110
	v_add_f32_e32 v111, 1.0, v101
	v_rcp_f32_e32 v111, v111
	v_add_f32_e32 v112, 1.0, v102
	v_mul_f32_e32 v114, v104, v105
	v_rcp_f32_e32 v112, v112
	v_add_f32_e32 v113, 1.0, v103
	v_mul_f32_e32 v114, v108, v114
	v_rcp_f32_e32 v113, v113
	v_mul_f32_e32 v114, v109, v114
	v_mul_f32_e32 v114, v110, v114
	v_mul_f32_e32 v114, v111, v114
	v_mul_f32_e32 v114, v112, v114
	v_cvt_pk_bf16_f32 v149, v176, v177
	v_cvt_pk_bf16_f32 v150, v170, v171
	v_cvt_pk_bf16_f32 v151, v172, v173
	v_mul_f32_e32 v115, v113, v114
	ds_bpermute_b32 v114, v251, v115
	s_waitcnt vmcnt(19)
; #define MFMA16(a, b, c) __builtin_amdgcn_mfma_f32_16x16x32_bf16((a), (b), (c), 0, 0, 0)
; DI unsigned pk2(float lo, float hi) { f32x2 v = {lo, hi}; bf16x2_t b = __builtin_convertvector(v, bf16x2_t); return __builtin_bit_cast(unsigned, b); }
; template <bool FULL>
; DI void sb_chunk(const SbFrag& f, int kb, int t, int quad, const bf16x8 (&qf)[2], f32x4 (&o)[4], float& carry) {
;   f32x4 s[2];
; #pragma unroll
;   for (int a = 0; a < 2; ++a) {
;     s[a] = MFMA16(f.k[a][0], qf[0], ((f32x4){0.f, 0.f, 0.f, 0.f}));
;     s[a] = MFMA16(f.k[a][1], qf[1], s[a]);
;   }
;   float beta[8], om[8];
;   float prod = 1.f;
; #pragma unroll
;   for (int idx = 0; idx < 8; ++idx) {
;     const float z2 = fminf(s[idx >> 2][idx & 3] * (0.125f * 1.44269504089f), 60.f);
;     const float e = __builtin_amdgcn_exp2f(z2);
;     const float r = __builtin_amdgcn_rcpf(1.f + e);
;     const bool val = FULL ? true : (kb + 8 * quad + idx < t);
;     om[idx] = val ? r : 1.f;
;     beta[idx] = val ? e * r : 0.f;
;     prod *= om[idx];
;   }
;   const float a1 = __shfl_xor(prod, 16), a2 = __shfl_xor(prod, 32), a3 = __shfl_xor(a1, 32);
;   const float higher = ((quad ^ 1) > quad ? a1 : 1.f) * ((quad ^ 2) > quad ? a2 : 1.f) * ((quad ^ 3) > quad ? a3 : 1.f);
;   float q = __builtin_amdgcn_exp2f(carry) * higher;
;   float wv[8];
; #pragma unroll
;     ...
;   carry += __builtin_amdgcn_logf((prod * a1) * (a2 * a3));
;   const bf16x8 pf = mk8((u32x4){pk2(wv[0], wv[1]), pk2(wv[2], wv[3]), pk2(wv[4], wv[5]), pk2(wv[6], wv[7])});
; #pragma unroll
;   for (int dt = 0; dt < 4; ++dt) o[dt] = MFMA16(f.v[dt], pf, o[dt]);
; }
	v_mfma_f32_16x16x32_bf16 v[48:51], v[68:71], v[148:151], v[48:51]
	v_mul_f32_e64 v2, v2, v104
	v_mul_f32_e64 v3, v3, v105
	v_pk_mul_f32 v[102:103], v[102:103], v[112:113]
	v_pk_mul_f32 v[100:101], v[100:101], v[110:111]
	s_waitcnt vmcnt(18)
	v_mfma_f32_16x16x32_bf16 v[44:47], v[72:75], v[148:151], v[44:47]
	s_waitcnt lgkmcnt(0)
	v_cndmask_b32_e64 v104, 1.0, v114, s[44:45]
	v_pk_mul_f32 v[106:107], v[106:107], v[108:109]
	s_waitcnt vmcnt(17)
	v_mfma_f32_16x16x32_bf16 v[24:27], v[60:63], v[148:151], v[24:27]
	s_waitcnt vmcnt(16)
	v_mfma_f32_16x16x32_bf16 v[20:23], v[52:55], v[148:151], v[20:23]
	ds_bpermute_b32 v149, v250, v115
	s_waitcnt lgkmcnt(0)
	ds_bpermute_b32 v148, v251, v149
	v_cndmask_b32_e32 v150, 1.0, v149, vcc
	v_mul_f32_e32 v104, v150, v104
	s_waitcnt lgkmcnt(0)
	v_cndmask_b32_e64 v150, 1.0, v148, s[46:47]
	v_mul_f32_e32 v104, v104, v150
	v_mul_f32_e32 v151, v0, v104
	v_mul_f32_e32 v150, v151, v113
	v_pk_mul_f32 v[168:169], v[150:151], v[102:103]
	v_mul_f32_e32 v103, v112, v150
	v_mul_f32_e32 v102, v111, v103
	v_pk_mul_f32 v[112:113], v[100:101], v[102:103]
	v_mul_f32_e32 v101, v110, v102
	v_mul_f32_e32 v100, v109, v101
	v_pk_mul_f32 v[102:103], v[106:107], v[100:101]
	v_mul_f32_e32 v101, v108, v100
	v_mul_f32_e32 v100, v105, v101
	v_pk_mul_f32 v[2:3], v[2:3], v[100:101]
	v_cvt_pk_bf16_f32 v101, v102, v103
	v_cvt_pk_bf16_f32 v100, v2, v3
	v_cvt_pk_bf16_f32 v102, v112, v113
	v_cvt_pk_bf16_f32 v103, v168, v169
	v_pk_mul_f32 v[2:3], v[180:181], v[182:183]
	s_nop 0
	v_mul_f32_e32 v0, v2, v3
	v_mfma_f32_16x16x32_bf16 v[8:11], v[60:63], v[100:103], v[8:11]
	v_mul_f32_e64 v60, v114, v148
	v_mul_f32_e64 v61, v115, v149
	v_log_f32_e32 v3, v0
	v_mul_f32_e32 v0, v60, v61
	v_mfma_f32_16x16x32_bf16 v[16:19], v[68:71], v[100:103], v[16:19]
	v_log_f32_e32 v2, v0
	v_mfma_f32_16x16x32_bf16 v[12:15], v[72:75], v[100:103], v[12:15]
	v_mfma_f32_16x16x32_bf16 v[4:7], v[52:55], v[100:103], v[4:7]
.LBB0_558:
	s_andn2_saveexec_b64 s[10:11], s[10:11]
	s_cbranch_execz .LBB0_560
	s_waitcnt vmcnt(23)
	v_mfma_f32_16x16x32_bf16 v[148:151], v[108:111], v[28:31], 0
	v_add_u32_e32 v2, v155, v166
	v_add_u32_e32 v169, 0x60, v2
	v_cmp_lt_i32_e64 s[8:9], v169, v156
	s_waitcnt vmcnt(22)
	v_mfma_f32_16x16x32_bf16 v[170:173], v[104:107], v[32:35], v[148:151]
	v_add_u32_e32 v175, 0x61, v2
	v_add_u32_e32 v177, 0x62, v2
	v_add_u32_e32 v179, 0x63, v2
	s_waitcnt vmcnt(21)
	v_mfma_f32_16x16x32_bf16 v[148:151], v[112:115], v[28:31], 0
	v_add_u32_e32 v181, 0x64, v2
	s_nop 1
	v_mul_f32_e32 v3, 0x3e38aa3b, v170
	v_min_f32_e32 v3, 0x42700000, v3
	v_exp_f32_e32 v3, v3
	v_mul_f32_e32 v172, 0x3e38aa3b, v172
	v_min_f32_e32 v172, 0x42700000, v172
	v_exp_f32_e32 v172, v172
	v_add_f32_e32 v170, 1.0, v3
	v_rcp_f32_e32 v170, v170
	v_mul_f32_e32 v173, 0x3e38aa3b, v173
	s_waitcnt vmcnt(20)
	v_mfma_f32_16x16x32_bf16 v[148:151], v[100:103], v[32:35], v[148:151]
	v_min_f32_e32 v173, 0x42700000, v173
	v_mul_f32_e32 v3, v3, v170
	v_cndmask_b32_e64 v174, 1.0, v170, s[8:9]
	v_cndmask_b32_e64 v170, 0, v3, s[8:9]
	v_mul_f32_e32 v3, 0x3e38aa3b, v171
	v_min_f32_e32 v3, 0x42700000, v3
	v_exp_f32_e32 v3, v3
	v_cmp_lt_i32_e64 s[8:9], v175, v156
	v_exp_f32_e32 v173, v173
	v_mul_f32_e32 v148, 0x3e38aa3b, v148
	v_add_f32_e32 v171, 1.0, v3
	v_rcp_f32_e32 v171, v171
	v_min_f32_e32 v148, 0x42700000, v148
	v_exp_f32_e32 v148, v148
	v_add_u32_e32 v183, 0x65, v2
	v_cndmask_b32_e64 v176, 1.0, v171, s[8:9]
	v_mul_f32_e32 v3, v3, v171
	v_cndmask_b32_e64 v171, 0, v3, s[8:9]
	v_mul_f32_e32 v3, v174, v176
	v_add_f32_e32 v174, 1.0, v172
	v_rcp_f32_e32 v174, v174
	v_cmp_lt_i32_e64 s[8:9], v177, v156
	v_add_u32_e32 v186, 0x66, v2
	v_add_u32_e32 v188, 0x67, v2
	v_cndmask_b32_e64 v178, 1.0, v174, s[8:9]
	v_mul_f32_e32 v172, v172, v174
	v_add_f32_e32 v174, 1.0, v173
	v_rcp_f32_e32 v174, v174
	v_cndmask_b32_e64 v172, 0, v172, s[8:9]
	v_cmp_lt_i32_e64 s[8:9], v179, v156
	v_mul_f32_e32 v3, v178, v3
	v_mul_f32_e32 v173, v173, v174
	v_cndmask_b32_e64 v180, 1.0, v174, s[8:9]
	v_add_f32_e32 v174, 1.0, v148
	v_rcp_f32_e32 v174, v174
	v_cndmask_b32_e64 v173, 0, v173, s[8:9]
	v_cmp_lt_i32_e64 s[8:9], v181, v156
	v_mul_f32_e32 v3, v180, v3
	v_mul_f32_e32 v148, v148, v174
	v_cndmask_b32_e64 v182, 1.0, v174, s[8:9]
	v_cndmask_b32_e64 v174, 0, v148, s[8:9]
	v_mul_f32_e32 v148, 0x3e38aa3b, v149
	v_min_f32_e32 v148, 0x42700000, v148
	v_exp_f32_e32 v148, v148
	v_cmp_lt_i32_e64 s[8:9], v183, v156
	v_mul_f32_e32 v3, v182, v3
	v_mfma_f32_16x16x32_bf16 v[108:111], v[108:111], v[36:39], 0
	v_add_f32_e32 v149, 1.0, v148
	v_rcp_f32_e32 v149, v149
	v_mfma_f32_16x16x32_bf16 v[104:107], v[104:107], v[40:43], v[108:111]
	v_mul_f32_e32 v148, v148, v149
	v_cndmask_b32_e64 v185, 0, v148, s[8:9]
	v_mul_f32_e32 v148, 0x3e38aa3b, v150
	v_min_f32_e32 v148, 0x42700000, v148
	v_exp_f32_e32 v148, v148
	v_cndmask_b32_e64 v184, 1.0, v149, s[8:9]
	v_cmp_lt_i32_e64 s[8:9], v186, v156
	v_mul_f32_e32 v3, v184, v3
	v_add_f32_e32 v149, 1.0, v148
	v_rcp_f32_e32 v149, v149
	v_mfma_f32_16x16x32_bf16 v[108:111], v[112:115], v[36:39], 0
	v_mul_f32_e32 v106, 0x3e38aa3b, v106
	v_min_f32_e32 v106, 0x42700000, v106
	v_mul_f32_e32 v148, v148, v149
	v_cndmask_b32_e64 v187, 0, v148, s[8:9]
	v_mul_f32_e32 v148, 0x3e38aa3b, v151
	v_min_f32_e32 v148, 0x42700000, v148
	v_exp_f32_e32 v148, v148
	v_cndmask_b32_e64 v150, 1.0, v149, s[8:9]
	v_cmp_lt_i32_e64 s[8:9], v188, v156
	v_mul_f32_e32 v3, v150, v3
	v_add_f32_e32 v149, 1.0, v148
	v_rcp_f32_e32 v149, v149
	v_mfma_f32_16x16x32_bf16 v[100:103], v[100:103], v[40:43], v[108:111]
	v_exp_f32_e32 v106, v106
	v_mul_f32_e32 v107, 0x3e38aa3b, v107
	v_mul_f32_e32 v2, v148, v149
	v_cndmask_b32_e64 v189, 0, v2, s[8:9]
	v_cndmask_b32_e64 v151, 1.0, v149, s[8:9]
	v_mul_f32_e32 v3, v151, v3
	v_min_f32_e32 v107, 0x42700000, v107
	ds_bpermute_b32 v149, v250, v3
	v_exp_f32_e32 v107, v107
	v_mul_f32_e32 v100, 0x3e38aa3b, v100
	ds_bpermute_b32 v2, v251, v3
	s_waitcnt lgkmcnt(1)
; #define MFMA16(a, b, c) __builtin_amdgcn_mfma_f32_16x16x32_bf16((a), (b), (c), 0, 0, 0)
; DI unsigned pk2(float lo, float hi) { f32x2 v = {lo, hi}; bf16x2_t b = __builtin_convertvector(v, bf16x2_t); return __builtin_bit_cast(unsigned, b); }
; template <bool FULL>
; DI void sb_chunk(const SbFrag& f, int kb, int t, int quad, const bf16x8 (&qf)[2], f32x4 (&o)[4], float& carry) {
;   f32x4 s[2];
; #pragma unroll
;   for (int a = 0; a < 2; ++a) {
;     s[a] = MFMA16(f.k[a][0], qf[0], ((f32x4){0.f, 0.f, 0.f, 0.f}));
;     s[a] = MFMA16(f.k[a][1], qf[1], s[a]);
;   }
;   float beta[8], om[8];
;   float prod = 1.f;
; #pragma unroll
;   for (int idx = 0; idx < 8; ++idx) {
;     const float z2 = fminf(s[idx >> 2][idx & 3] * (0.125f * 1.44269504089f), 60.f);
;     const float e = __builtin_amdgcn_exp2f(z2);
;     const float r = __builtin_amdgcn_rcpf(1.f + e);
;     const bool val = FULL ? true : (kb + 8 * quad + idx < t);
;     om[idx] = val ? r : 1.f;
;     beta[idx] = val ? e * r : 0.f;
;     prod *= om[idx];
;   }
;   const float a1 = __shfl_xor(prod, 16), a2 = __shfl_xor(prod, 32), a3 = __shfl_xor(a1, 32);
;   const float higher = ((quad ^ 1) > quad ? a1 : 1.f) * ((quad ^ 2) > quad ? a2 : 1.f) * ((quad ^ 3) > quad ? a3 : 1.f);
;   float q = __builtin_amdgcn_exp2f(carry) * higher;
;   float wv[8];
; #pragma unroll
;     ...
;   carry += __builtin_amdgcn_logf((prod * a1) * (a2 * a3));
;   const bf16x8 pf = mk8((u32x4){pk2(wv[0], wv[1]), pk2(wv[2], wv[3]), pk2(wv[4], wv[5]), pk2(wv[6], wv[7])});
; #pragma unroll
;   for (int dt = 0; dt < 4; ++dt) o[dt] = MFMA16(f.v[dt], pf, o[dt]);
; }
	ds_bpermute_b32 v148, v251, v149
	v_cmp_lt_i32_e64 s[8:9], v169, v152
	v_min_f32_e32 v100, 0x42700000, v100
	v_exp_f32_e32 v100, v100
	s_waitcnt lgkmcnt(1)
	v_cndmask_b32_e64 v192, 1.0, v2, s[44:45]
	s_waitcnt lgkmcnt(0)
	v_pk_mul_f32 v[2:3], v[2:3], v[148:149]
	v_mul_f32_e32 v101, 0x3e38aa3b, v101
	v_mul_f32_e32 v2, v2, v3
	v_log_f32_e32 v3, v2
	v_mul_f32_e32 v2, 0x3e38aa3b, v104
	v_min_f32_e32 v2, 0x42700000, v2
	v_exp_f32_e32 v2, v2
	v_min_f32_e32 v101, 0x42700000, v101
	v_exp_f32_e32 v101, v101
	v_cndmask_b32_e32 v193, 1.0, v149, vcc
	v_add_f32_e32 v104, 1.0, v2
	v_rcp_f32_e32 v104, v104
	v_mul_f32_e32 v192, v193, v192
	v_cndmask_b32_e64 v193, 1.0, v148, s[46:47]
	v_mul_f32_e32 v192, v192, v193
	v_cndmask_b32_e64 v108, 1.0, v104, s[8:9]
	v_mul_f32_e32 v2, v2, v104
	v_mul_f32_e32 v104, 0x3e38aa3b, v105
	v_min_f32_e32 v104, 0x42700000, v104
	v_exp_f32_e32 v104, v104
	v_cndmask_b32_e64 v2, 0, v2, s[8:9]
	v_cmp_lt_i32_e64 s[8:9], v175, v152
	v_mul_f32_e32 v168, v168, v192
	v_add_f32_e32 v105, 1.0, v104
	v_rcp_f32_e32 v105, v105
	v_mul_f32_e32 v151, v151, v168
	v_mul_f32_e32 v150, v150, v151
	v_mul_f32_e32 v189, v168, v189
	v_cndmask_b32_e64 v109, 1.0, v105, s[8:9]
	v_mul_f32_e32 v104, v104, v105
	v_mul_f32_e32 v105, v108, v109
	v_add_f32_e32 v108, 1.0, v106
	v_rcp_f32_e32 v108, v108
	v_cndmask_b32_e64 v104, 0, v104, s[8:9]
	v_cmp_lt_i32_e64 s[8:9], v177, v152
	v_mul_f32_e32 v168, v187, v151
	v_mul_f32_e32 v106, v106, v108
	v_cndmask_b32_e64 v110, 1.0, v108, s[8:9]
	v_add_f32_e32 v108, 1.0, v107
	v_rcp_f32_e32 v108, v108
	v_cndmask_b32_e64 v106, 0, v106, s[8:9]
	v_cmp_lt_i32_e64 s[8:9], v179, v152
	v_mul_f32_e32 v105, v110, v105
	v_mul_f32_e32 v107, v107, v108
	v_cndmask_b32_e64 v111, 1.0, v108, s[8:9]
	v_add_f32_e32 v108, 1.0, v100
	v_rcp_f32_e32 v108, v108
	v_cndmask_b32_e64 v107, 0, v107, s[8:9]
	v_cmp_lt_i32_e64 s[8:9], v181, v152
	v_mul_f32_e32 v105, v111, v105
	v_mul_f32_e32 v100, v100, v108
	v_cndmask_b32_e64 v112, 1.0, v108, s[8:9]
	v_cndmask_b32_e64 v108, 0, v100, s[8:9]
	v_mul_f32_e32 v100, v112, v105
	v_add_f32_e32 v105, 1.0, v101
	v_rcp_f32_e32 v105, v105
	v_cmp_lt_i32_e64 s[8:9], v183, v152
	v_mul_f32_e32 v151, v185, v150
	v_mul_f32_e32 v150, v184, v150
	v_mul_f32_e32 v101, v101, v105
	v_cndmask_b32_e64 v113, 1.0, v105, s[8:9]
	v_cndmask_b32_e64 v105, 0, v101, s[8:9]
	v_mul_f32_e32 v101, 0x3e38aa3b, v102
	v_min_f32_e32 v101, 0x42700000, v101
	v_exp_f32_e32 v101, v101
	v_cmp_lt_i32_e64 s[8:9], v186, v152
	v_mul_f32_e32 v174, v174, v150
	v_mul_f32_e32 v150, v182, v150
	v_add_f32_e32 v102, 1.0, v101
	v_rcp_f32_e32 v102, v102
	v_mul_f32_e32 v173, v173, v150
	v_mul_f32_e32 v150, v180, v150
	v_mul_f32_e32 v172, v172, v150
	v_mul_f32_e32 v101, v101, v102
	v_cndmask_b32_e64 v115, 0, v101, s[8:9]
	v_mul_f32_e32 v101, 0x3e38aa3b, v103
	v_min_f32_e32 v101, 0x42700000, v101
	v_exp_f32_e32 v101, v101
	v_cndmask_b32_e64 v114, 1.0, v102, s[8:9]
	v_mul_f32_e32 v150, v178, v150
	v_mul_f32_e32 v171, v171, v150
	v_add_f32_e32 v102, 1.0, v101
	v_rcp_f32_e32 v102, v102
	v_mul_f32_e32 v150, v176, v150
	v_mul_f32_e32 v150, v170, v150
	v_cvt_pk_bf16_f32 v148, v150, v171
	v_cvt_pk_bf16_f32 v149, v172, v173
	v_cvt_pk_bf16_f32 v150, v174, v151
	v_cvt_pk_bf16_f32 v151, v168, v189
	v_mul_f32_e32 v100, v113, v100
	v_cmp_lt_i32_e64 s[8:9], v188, v152
	s_waitcnt vmcnt(19)
	v_mfma_f32_16x16x32_bf16 v[48:51], v[68:71], v[148:151], v[48:51]
	v_mul_f32_e32 v100, v114, v100
	v_mul_f32_e32 v101, v101, v102
	s_waitcnt vmcnt(18)
	v_mfma_f32_16x16x32_bf16 v[44:47], v[72:75], v[148:151], v[44:47]
	s_waitcnt vmcnt(17)
	v_mfma_f32_16x16x32_bf16 v[24:27], v[60:63], v[148:151], v[24:27]
	s_waitcnt vmcnt(16)
	v_mfma_f32_16x16x32_bf16 v[20:23], v[52:55], v[148:151], v[20:23]
	v_cndmask_b32_e64 v148, 1.0, v102, s[8:9]
	v_cndmask_b32_e64 v149, 0, v101, s[8:9]
	v_mul_f32_e32 v101, v148, v100
	ds_bpermute_b32 v103, v250, v101
	ds_bpermute_b32 v100, v251, v101
	s_waitcnt lgkmcnt(1)
	ds_bpermute_b32 v102, v251, v103
	s_waitcnt lgkmcnt(1)
	v_cndmask_b32_e64 v150, 1.0, v100, s[44:45]
	v_cndmask_b32_e32 v151, 1.0, v103, vcc
	v_mul_f32_e32 v150, v151, v150
	s_waitcnt lgkmcnt(0)
	v_cndmask_b32_e64 v151, 1.0, v102, s[46:47]
	v_mul_f32_e32 v150, v150, v151
	v_mul_f32_e32 v0, v0, v150
	v_mul_f32_e32 v149, v0, v149
	v_mul_f32_e32 v0, v0, v148
	v_mul_f32_e32 v115, v0, v115
	v_mul_f32_e32 v0, v114, v0
	v_mul_f32_e32 v105, v105, v0
	v_mul_f32_e32 v0, v113, v0
	v_mul_f32_e32 v108, v108, v0
	v_mul_f32_e32 v0, v112, v0
	v_mul_f32_e32 v107, v107, v0
	v_mul_f32_e32 v0, v111, v0
	v_mul_f32_e32 v106, v106, v0
	v_mul_f32_e32 v0, v110, v0
	v_mul_f32_e32 v104, v104, v0
	v_mul_f32_e32 v0, v109, v0
	v_mul_f32_e32 v0, v2, v0
	v_pk_mul_f32 v[100:101], v[100:101], v[102:103]
	v_cvt_pk_bf16_f32 v102, v108, v105
	v_mul_f32_e32 v2, v100, v101
	v_cvt_pk_bf16_f32 v100, v0, v104
	v_cvt_pk_bf16_f32 v101, v106, v107
	v_cvt_pk_bf16_f32 v103, v115, v149
	v_log_f32_e32 v2, v2
	s_nop 0
	v_mfma_f32_16x16x32_bf16 v[16:19], v[68:71], v[100:103], v[16:19]
	v_mfma_f32_16x16x32_bf16 v[12:15], v[72:75], v[100:103], v[12:15]
	v_mfma_f32_16x16x32_bf16 v[8:11], v[60:63], v[100:103], v[8:11]
	v_mfma_f32_16x16x32_bf16 v[4:7], v[52:55], v[100:103], v[4:7]
; #define MFMA16(a, b, c) __builtin_amdgcn_mfma_f32_16x16x32_bf16((a), (b), (c), 0, 0, 0)
; DI unsigned pk2(float lo, float hi) { f32x2 v = {lo, hi}; bf16x2_t b = __builtin_convertvector(v, bf16x2_t); return __builtin_bit_cast(unsigned, b); }
; #define SB_STEP(F, KB) (((KB) + 32 <= t0) ? (sb_chunk<true>(F, KB, tA, quad, qa, oa, ca), sb_chunk<true>(F, KB, tB, quad, qb, ob, cb)) : (sb_chunk<false>(F, KB, tA, quad, qa, oa, ca), sb_chunk<false>(F, KB, tB, quad, qb, ob, cb)), __all(ca < -160.f && cb < -160.f))
; template <bool FULL>
; DI void sb_chunk(const SbFrag& f, int kb, int t, int quad, const bf16x8 (&qf)[2], f32x4 (&o)[4], float& carry) {
;   f32x4 s[2];
; #pragma unroll
;   for (int a = 0; a < 2; ++a) {
;     s[a] = MFMA16(f.k[a][0], qf[0], ((f32x4){0.f, 0.f, 0.f, 0.f}));
;     s[a] = MFMA16(f.k[a][1], qf[1], s[a]);
;   }
;   float beta[8], om[8];
;   float prod = 1.f;
; #pragma unroll
;   for (int idx = 0; idx < 8; ++idx) {
;     const float z2 = fminf(s[idx >> 2][idx & 3] * (0.125f * 1.44269504089f), 60.f);
;     const float e = __builtin_amdgcn_exp2f(z2);
;     const float r = __builtin_amdgcn_rcpf(1.f + e);
;     const bool val = FULL ? true : (kb + 8 * quad + idx < t);
;     om[idx] = val ? r : 1.f;
;     beta[idx] = val ? e * r : 0.f;
;     prod *= om[idx];
;   }
;   const float a1 = __shfl_xor(prod, 16), a2 = __shfl_xor(prod, 32), a3 = __shfl_xor(a1, 32);
;   const float higher = ((quad ^ 1) > quad ? a1 : 1.f) * ((quad ^ 2) > quad ? a2 : 1.f) * ((quad ^ 3) > quad ? a3 : 1.f);
;   float q = __builtin_amdgcn_exp2f(carry) * higher;
;   float wv[8];
; #pragma unroll
;     ...
;   carry += __builtin_amdgcn_logf((prod * a1) * (a2 * a3));
;   const bf16x8 pf = mk8((u32x4){pk2(wv[0], wv[1]), pk2(wv[2], wv[3]), pk2(wv[4], wv[5]), pk2(wv[6], wv[7])});
; #pragma unroll
;   for (int dt = 0; dt < 4; ++dt) o[dt] = MFMA16(f.v[dt], pf, o[dt]);
; }
; DI void sb_attn_wave(const Params& p, int b, int h, int t0, bf16_t* ybase) {
;     ...
;   while (true) {
;     sb_load(f2, kp0, vp0, max(kb - 64, 0));
;     if (SB_STEP(f0, kb) || kb < 32) break;
;     sb_load(f0, kp0, vp0, max(kb - 96, 0));
;     if (SB_STEP(f1, kb - 32) || kb < 64) break;
.LBB0_560:
	s_or_b64 exec, exec, s[10:11]
	v_pk_add_f32 v[2:3], v[162:163], v[2:3]
	s_nop 0
	v_cmp_gt_f32_e64 s[8:9], s31, v3
	v_cmp_gt_f32_e64 s[10:11], s31, v2
	s_and_b64 s[8:9], s[8:9], s[10:11]
	v_cndmask_b32_e64 v0, 0, 1, s[8:9]
	v_cmp_ne_u32_e64 s[8:9], 0, v0
	s_cmp_lg_u64 s[8:9], exec
	s_cselect_b64 s[10:11], -1, 0
	v_cmp_lt_i32_e64 s[8:9], 31, v167
	s_and_b64 s[10:11], s[8:9], s[10:11]
	s_mov_b64 s[8:9], -1
	s_and_saveexec_b64 s[12:13], s[10:11]
	s_cbranch_execz .LBB0_555
	v_max_i32_e32 v0, 0, v166
	s_waitcnt vmcnt(16)
	v_lshlrev_b64 v[52:53], 7, v[0:1]
	v_lshl_add_u64 v[54:55], v[158:159], 0, v[52:53]
	v_or_b32_e32 v0, 4, v0
	global_load_dwordx4 v[108:111], v[54:55], off
	global_load_dwordx4 v[104:107], v[54:55], off offset:64
	v_lshlrev_b64 v[54:55], 7, v[0:1]
	v_lshl_add_u64 v[54:55], v[158:159], 0, v[54:55]
	v_lshl_add_u64 v[52:53], v[160:161], 0, v[52:53]
	global_load_dwordx4 v[112:115], v[54:55], off
	global_load_dwordx4 v[100:103], v[54:55], off offset:64
	global_load_dwordx4 v[68:71], v[52:53], off
	global_load_dwordx4 v[72:75], v[52:53], off offset:1024
	global_load_dwordx4 v[60:63], v[52:53], off offset:2048
	s_nop 0
	global_load_dwordx4 v[52:55], v[52:53], off offset:3072
	v_exp_f32_e32 v162, v3
	v_exp_f32_e32 v0, v2
	v_cmp_le_i32_e64 s[8:9], v167, v154
	s_and_saveexec_b64 s[10:11], s[8:9]
	s_xor_b64 s[10:11], exec, s[10:11]
	s_cbranch_execz .LBB0_563
	s_waitcnt vmcnt(23)
	v_mfma_f32_16x16x32_bf16 v[148:151], v[120:123], v[28:31], 0
	s_waitcnt vmcnt(21)
	v_mfma_f32_16x16x32_bf16 v[168:171], v[128:131], v[28:31], 0
	v_mfma_f32_16x16x32_bf16 v[148:151], v[116:119], v[32:35], v[148:151]
	s_waitcnt vmcnt(20)
	v_mfma_f32_16x16x32_bf16 v[168:171], v[124:127], v[32:35], v[168:171]
	v_mfma_f32_16x16x32_bf16 v[120:123], v[120:123], v[36:39], 0
	s_nop 4
	v_mul_f32_e32 v148, 0x3e38aa3b, v148
	v_mul_f32_e32 v150, 0x3e38aa3b, v150
	v_min_f32_e32 v148, 0x42700000, v148
	v_exp_f32_e32 v148, v148
	v_min_f32_e32 v150, 0x42700000, v150
	v_mul_f32_e32 v151, 0x3e38aa3b, v151
	v_exp_f32_e32 v150, v150
	v_min_f32_e32 v151, 0x42700000, v151
	v_mul_f32_e32 v168, 0x3e38aa3b, v168
	v_exp_f32_e32 v151, v151
	v_min_f32_e32 v168, 0x42700000, v168
	v_mul_f32_e32 v169, 0x3e38aa3b, v169
	v_exp_f32_e32 v168, v168
	v_min_f32_e32 v169, 0x42700000, v169
	v_mul_f32_e32 v170, 0x3e38aa3b, v170
	v_add_f32_e32 v163, 1.0, v148
	v_exp_f32_e32 v169, v169
	v_min_f32_e32 v170, 0x42700000, v170
	v_mul_f32_e32 v171, 0x3e38aa3b, v171
	v_rcp_f32_e32 v172, v163
	v_add_f32_e32 v163, 1.0, v150
	v_exp_f32_e32 v170, v170
	v_min_f32_e32 v171, 0x42700000, v171
	v_mul_f32_e32 v149, 0x3e38aa3b, v149
	v_rcp_f32_e32 v174, v163
	v_add_f32_e32 v163, 1.0, v151
	v_exp_f32_e32 v171, v171
	v_min_f32_e32 v149, 0x42700000, v149
	v_rcp_f32_e32 v175, v163
	v_add_f32_e32 v163, 1.0, v168
	v_exp_f32_e32 v149, v149
	v_rcp_f32_e32 v176, v163
	v_add_f32_e32 v163, 1.0, v169
	v_rcp_f32_e32 v177, v163
	v_add_f32_e32 v163, 1.0, v170
	v_rcp_f32_e32 v178, v163
	v_add_f32_e32 v163, 1.0, v171
	v_rcp_f32_e32 v179, v163
	v_add_f32_e32 v173, 1.0, v149
	v_rcp_f32_e32 v173, v173
	v_mfma_f32_16x16x32_bf16 v[116:119], v[116:119], v[40:43], v[120:123]
	v_mfma_f32_16x16x32_bf16 v[120:123], v[128:131], v[36:39], 0
	v_mul_f32_e64 v148, v148, v172
	v_mul_f32_e64 v149, v149, v173
	v_mul_f32_e32 v163, v172, v173
	v_mul_f32_e32 v163, v174, v163
	v_mul_f32_e32 v163, v175, v163
	v_mul_f32_e32 v163, v176, v163
	v_mul_f32_e32 v163, v177, v163
	v_mul_f32_e32 v163, v178, v163
	v_mul_f32_e32 v181, v179, v163
	ds_bpermute_b32 v183, v250, v181
	ds_bpermute_b32 v180, v251, v181
	v_mfma_f32_16x16x32_bf16 v[120:123], v[124:127], v[40:43], v[120:123]
	v_mul_f32_e32 v116, 0x3e38aa3b, v116
	v_mul_f32_e32 v117, 0x3e38aa3b, v117
	s_waitcnt lgkmcnt(1)
	ds_bpermute_b32 v182, v251, v183
	s_waitcnt lgkmcnt(1)
	v_cndmask_b32_e64 v163, 1.0, v180, s[44:45]
	v_cndmask_b32_e32 v172, 1.0, v183, vcc
	v_mul_f32_e32 v163, v172, v163
	v_min_f32_e32 v116, 0x42700000, v116
	s_waitcnt lgkmcnt(0)
	v_cndmask_b32_e64 v172, 1.0, v182, s[46:47]
	v_mul_f32_e32 v163, v163, v172
	v_mul_f32_e32 v163, v162, v163
	v_min_f32_e32 v117, 0x42700000, v117
	v_mul_f32_e32 v118, 0x3e38aa3b, v118
	v_pk_mul_f32 v[170:171], v[170:171], v[178:179]
	v_mul_f32_e32 v162, v179, v163
	v_exp_f32_e32 v116, v116
	v_exp_f32_e32 v117, v117
	v_min_f32_e32 v118, 0x42700000, v118
	v_mul_f32_e32 v119, 0x3e38aa3b, v119
	v_pk_mul_f32 v[170:171], v[170:171], v[162:163]
	v_mul_f32_e32 v163, v178, v162
	v_exp_f32_e32 v118, v118
	v_min_f32_e32 v119, 0x42700000, v119
	v_mul_f32_e32 v120, 0x3e38aa3b, v120
	v_pk_mul_f32 v[168:169], v[168:169], v[176:177]
	v_mul_f32_e32 v162, v177, v163
	v_exp_f32_e32 v119, v119
	v_min_f32_e32 v120, 0x42700000, v120
	v_mul_f32_e32 v121, 0x3e38aa3b, v121
	v_pk_mul_f32 v[168:169], v[168:169], v[162:163]
	v_mul_f32_e32 v163, v176, v162
	v_exp_f32_e32 v120, v120
	v_min_f32_e32 v121, 0x42700000, v121
	v_mul_f32_e32 v122, 0x3e38aa3b, v122
	v_pk_mul_f32 v[150:151], v[150:151], v[174:175]
	v_mul_f32_e32 v162, v175, v163
	v_add_f32_e32 v124, 1.0, v116
	v_add_f32_e32 v125, 1.0, v117
	v_exp_f32_e32 v121, v121
	v_min_f32_e32 v122, 0x42700000, v122
	v_mul_f32_e32 v123, 0x3e38aa3b, v123
	v_pk_mul_f32 v[150:151], v[150:151], v[162:163]
	v_mul_f32_e32 v163, v174, v162
	v_rcp_f32_e32 v124, v124
	v_rcp_f32_e32 v125, v125
	v_add_f32_e32 v126, 1.0, v118
	v_exp_f32_e32 v122, v122
	v_min_f32_e32 v123, 0x42700000, v123
	v_mul_f32_e32 v162, v173, v163
	v_rcp_f32_e32 v126, v126
	v_add_f32_e32 v127, 1.0, v119
	v_exp_f32_e32 v123, v123
	v_pk_mul_f32 v[148:149], v[148:149], v[162:163]
	v_rcp_f32_e32 v127, v127
	v_add_f32_e32 v128, 1.0, v120
	v_cvt_pk_bf16_f32 v148, v148, v149
	v_cvt_pk_bf16_f32 v149, v150, v151
	v_cvt_pk_bf16_f32 v150, v168, v169
	v_cvt_pk_bf16_f32 v151, v170, v171
	v_rcp_f32_e32 v128, v128
	v_add_f32_e32 v129, 1.0, v121
	s_waitcnt vmcnt(19)
; #define MFMA16(a, b, c) __builtin_amdgcn_mfma_f32_16x16x32_bf16((a), (b), (c), 0, 0, 0)
; DI unsigned pk2(float lo, float hi) { f32x2 v = {lo, hi}; bf16x2_t b = __builtin_convertvector(v, bf16x2_t); return __builtin_bit_cast(unsigned, b); }
; template <bool FULL>
; DI void sb_chunk(const SbFrag& f, int kb, int t, int quad, const bf16x8 (&qf)[2], f32x4 (&o)[4], float& carry) {
;   f32x4 s[2];
; #pragma unroll
;   for (int a = 0; a < 2; ++a) {
;     s[a] = MFMA16(f.k[a][0], qf[0], ((f32x4){0.f, 0.f, 0.f, 0.f}));
;     s[a] = MFMA16(f.k[a][1], qf[1], s[a]);
;   }
;   float beta[8], om[8];
;   float prod = 1.f;
; #pragma unroll
;   for (int idx = 0; idx < 8; ++idx) {
;     const float z2 = fminf(s[idx >> 2][idx & 3] * (0.125f * 1.44269504089f), 60.f);
;     const float e = __builtin_amdgcn_exp2f(z2);
;     const float r = __builtin_amdgcn_rcpf(1.f + e);
;     const bool val = FULL ? true : (kb + 8 * quad + idx < t);
;     om[idx] = val ? r : 1.f;
;     beta[idx] = val ? e * r : 0.f;
;     prod *= om[idx];
;   }
;   const float a1 = __shfl_xor(prod, 16), a2 = __shfl_xor(prod, 32), a3 = __shfl_xor(a1, 32);
;   const float higher = ((quad ^ 1) > quad ? a1 : 1.f) * ((quad ^ 2) > quad ? a2 : 1.f) * ((quad ^ 3) > quad ? a3 : 1.f);
;   float q = __builtin_amdgcn_exp2f(carry) * higher;
;   float wv[8];
; #pragma unroll
;     ...
;   carry += __builtin_amdgcn_logf((prod * a1) * (a2 * a3));
;   const bf16x8 pf = mk8((u32x4){pk2(wv[0], wv[1]), pk2(wv[2], wv[3]), pk2(wv[4], wv[5]), pk2(wv[6], wv[7])});
; #pragma unroll
;   for (int dt = 0; dt < 4; ++dt) o[dt] = MFMA16(f.v[dt], pf, o[dt]);
; }
	v_mfma_f32_16x16x32_bf16 v[48:51], v[80:83], v[148:151], v[48:51]
	v_rcp_f32_e32 v129, v129
	v_add_f32_e32 v130, 1.0, v122
	v_rcp_f32_e32 v130, v130
	s_waitcnt vmcnt(18)
	v_mfma_f32_16x16x32_bf16 v[44:47], v[76:79], v[148:151], v[44:47]
	v_add_f32_e32 v131, 1.0, v123
	v_rcp_f32_e32 v131, v131
	v_pk_mul_f32 v[116:117], v[116:117], v[124:125]
	s_waitcnt vmcnt(17)
	v_mfma_f32_16x16x32_bf16 v[24:27], v[64:67], v[148:151], v[24:27]
	v_mul_f32_e64 v120, v120, v128
	v_mul_f32_e64 v121, v121, v129
	v_pk_mul_f32 v[122:123], v[122:123], v[130:131]
	v_pk_mul_f32 v[118:119], v[118:119], v[126:127]
	s_waitcnt vmcnt(16)
	v_mfma_f32_16x16x32_bf16 v[20:23], v[56:59], v[148:151], v[20:23]
	v_mul_f32_e32 v148, v124, v125
	v_mul_f32_e32 v148, v126, v148
	v_mul_f32_e32 v148, v127, v148
	v_mul_f32_e32 v148, v128, v148
	v_mul_f32_e32 v148, v129, v148
	v_mul_f32_e32 v148, v130, v148
	v_mul_f32_e32 v151, v131, v148
	ds_bpermute_b32 v163, v250, v151
	ds_bpermute_b32 v150, v251, v151
	s_waitcnt lgkmcnt(1)
	ds_bpermute_b32 v162, v251, v163
	s_waitcnt lgkmcnt(1)
	v_cndmask_b32_e64 v124, 1.0, v150, s[44:45]
	v_cndmask_b32_e32 v148, 1.0, v163, vcc
	v_mul_f32_e32 v124, v148, v124
	s_waitcnt lgkmcnt(0)
	v_cndmask_b32_e64 v148, 1.0, v162, s[46:47]
	v_mul_f32_e32 v124, v124, v148
	v_mul_f32_e32 v149, v0, v124
	v_mul_f32_e32 v148, v149, v131
	v_mul_f32_e32 v131, v130, v148
	v_mul_f32_e32 v130, v129, v131
	v_mul_f32_e32 v129, v128, v130
	v_mul_f32_e32 v128, v127, v129
	v_mul_f32_e32 v127, v126, v128
	v_mul_f32_e32 v126, v125, v127
	v_pk_mul_f32 v[122:123], v[148:149], v[122:123]
	v_pk_mul_f32 v[120:121], v[120:121], v[130:131]
	v_pk_mul_f32 v[118:119], v[118:119], v[128:129]
	v_pk_mul_f32 v[116:117], v[116:117], v[126:127]
	s_nop 0
	v_cvt_pk_bf16_f32 v116, v116, v117
	v_cvt_pk_bf16_f32 v117, v118, v119
	v_cvt_pk_bf16_f32 v118, v120, v121
	v_cvt_pk_bf16_f32 v119, v122, v123
	s_nop 1
	v_mfma_f32_16x16x32_bf16 v[12:15], v[76:79], v[116:119], v[12:15]
	v_mul_f32_e64 v76, v180, v182
	v_mul_f32_e64 v77, v181, v183
	v_mul_f32_e32 v0, v76, v77
	v_mfma_f32_16x16x32_bf16 v[8:11], v[64:67], v[116:119], v[8:11]
	v_mul_f32_e64 v64, v150, v162
	v_mul_f32_e64 v65, v151, v163
	v_log_f32_e32 v149, v0
	v_mul_f32_e32 v0, v64, v65
	v_mfma_f32_16x16x32_bf16 v[16:19], v[80:83], v[116:119], v[16:19]
	v_log_f32_e32 v148, v0
	v_mfma_f32_16x16x32_bf16 v[4:7], v[56:59], v[116:119], v[4:7]
.LBB0_563:
	s_andn2_saveexec_b64 s[10:11], s[10:11]
	s_cbranch_execz .LBB0_565
	s_waitcnt vmcnt(23)
	v_mfma_f32_16x16x32_bf16 v[148:151], v[120:123], v[28:31], 0
	v_add_u32_e32 v163, v155, v166
	v_add_u32_e32 v172, 64, v163
	v_cmp_lt_i32_e64 s[8:9], v172, v156
	s_waitcnt vmcnt(22)
	v_mfma_f32_16x16x32_bf16 v[168:171], v[116:119], v[32:35], v[148:151]
	v_add_u32_e32 v175, 0x41, v163
	v_add_u32_e32 v177, 0x42, v163
	v_add_u32_e32 v179, 0x43, v163
	s_waitcnt vmcnt(21)
	v_mfma_f32_16x16x32_bf16 v[148:151], v[128:131], v[28:31], 0
	v_add_u32_e32 v181, 0x44, v163
	s_nop 1
	v_mul_f32_e32 v168, 0x3e38aa3b, v168
	v_min_f32_e32 v168, 0x42700000, v168
	v_exp_f32_e32 v168, v168
	v_mul_f32_e32 v169, 0x3e38aa3b, v169
	v_min_f32_e32 v169, 0x42700000, v169
	v_exp_f32_e32 v169, v169
	v_add_f32_e32 v173, 1.0, v168
	v_rcp_f32_e32 v173, v173
	v_mul_f32_e32 v170, 0x3e38aa3b, v170
	v_min_f32_e32 v170, 0x42700000, v170
	v_exp_f32_e32 v170, v170
	v_cndmask_b32_e64 v174, 1.0, v173, s[8:9]
	v_mul_f32_e32 v168, v168, v173
	v_add_f32_e32 v173, 1.0, v169
	v_rcp_f32_e32 v173, v173
	v_cndmask_b32_e64 v168, 0, v168, s[8:9]
	v_cmp_lt_i32_e64 s[8:9], v175, v156
	v_mul_f32_e32 v171, 0x3e38aa3b, v171
	s_waitcnt vmcnt(20)
	v_mfma_f32_16x16x32_bf16 v[148:151], v[124:127], v[32:35], v[148:151]
	v_cndmask_b32_e64 v176, 1.0, v173, s[8:9]
	v_mul_f32_e32 v169, v169, v173
	v_mul_f32_e32 v173, v174, v176
	v_add_f32_e32 v174, 1.0, v170
	v_min_f32_e32 v171, 0x42700000, v171
	v_rcp_f32_e32 v174, v174
	v_exp_f32_e32 v171, v171
	v_cndmask_b32_e64 v169, 0, v169, s[8:9]
	v_cmp_lt_i32_e64 s[8:9], v177, v156
	v_mul_f32_e32 v148, 0x3e38aa3b, v148
	v_mul_f32_e32 v170, v170, v174
	v_cndmask_b32_e64 v178, 1.0, v174, s[8:9]
	v_add_f32_e32 v174, 1.0, v171
	v_min_f32_e32 v148, 0x42700000, v148
	v_rcp_f32_e32 v174, v174
	v_exp_f32_e32 v148, v148
	v_cndmask_b32_e64 v170, 0, v170, s[8:9]
	v_cmp_lt_i32_e64 s[8:9], v179, v156
	v_mul_f32_e32 v171, v171, v174
	v_mul_f32_e32 v149, 0x3e38aa3b, v149
	v_cndmask_b32_e64 v180, 1.0, v174, s[8:9]
	v_add_f32_e32 v174, 1.0, v148
	v_rcp_f32_e32 v174, v174
	v_min_f32_e32 v149, 0x42700000, v149
	v_exp_f32_e32 v149, v149
	v_mul_f32_e32 v173, v178, v173
	v_cndmask_b32_e64 v171, 0, v171, s[8:9]
	v_cmp_lt_i32_e64 s[8:9], v181, v156
	v_mul_f32_e32 v173, v180, v173
	v_mul_f32_e32 v148, v148, v174
	v_cndmask_b32_e64 v182, 1.0, v174, s[8:9]
	v_cndmask_b32_e64 v174, 0, v148, s[8:9]
	v_mul_f32_e32 v148, v182, v173
	v_add_f32_e32 v173, 1.0, v149
	v_rcp_f32_e32 v173, v173
	v_add_u32_e32 v183, 0x45, v163
	v_cmp_lt_i32_e64 s[8:9], v183, v156
	v_add_u32_e32 v185, 0x46, v163
	v_mul_f32_e32 v149, v149, v173
	v_cndmask_b32_e64 v184, 1.0, v173, s[8:9]
	v_cndmask_b32_e64 v173, 0, v149, s[8:9]
	v_mul_f32_e32 v149, 0x3e38aa3b, v150
	v_min_f32_e32 v149, 0x42700000, v149
	v_exp_f32_e32 v149, v149
	v_cmp_lt_i32_e64 s[8:9], v185, v156
	v_mfma_f32_16x16x32_bf16 v[120:123], v[120:123], v[36:39], 0
	v_add_u32_e32 v163, 0x47, v163
	v_add_f32_e32 v150, 1.0, v149
	v_rcp_f32_e32 v150, v150
	v_mfma_f32_16x16x32_bf16 v[120:123], v[116:119], v[40:43], v[120:123]
	v_mul_f32_e32 v148, v184, v148
	v_mul_f32_e32 v149, v149, v150
	v_cndmask_b32_e64 v187, 0, v149, s[8:9]
	v_mul_f32_e32 v149, 0x3e38aa3b, v151
	v_min_f32_e32 v149, 0x42700000, v149
	v_exp_f32_e32 v149, v149
; #define MFMA16(a, b, c) __builtin_amdgcn_mfma_f32_16x16x32_bf16((a), (b), (c), 0, 0, 0)
; DI unsigned pk2(float lo, float hi) { f32x2 v = {lo, hi}; bf16x2_t b = __builtin_convertvector(v, bf16x2_t); return __builtin_bit_cast(unsigned, b); }
; template <bool FULL>
; DI void sb_chunk(const SbFrag& f, int kb, int t, int quad, const bf16x8 (&qf)[2], f32x4 (&o)[4], float& carry) {
;   f32x4 s[2];
; #pragma unroll
;   for (int a = 0; a < 2; ++a) {
;     s[a] = MFMA16(f.k[a][0], qf[0], ((f32x4){0.f, 0.f, 0.f, 0.f}));
;     s[a] = MFMA16(f.k[a][1], qf[1], s[a]);
;   }
;   float beta[8], om[8];
;   float prod = 1.f;
; #pragma unroll
;   for (int idx = 0; idx < 8; ++idx) {
;     const float z2 = fminf(s[idx >> 2][idx & 3] * (0.125f * 1.44269504089f), 60.f);
;     const float e = __builtin_amdgcn_exp2f(z2);
;     const float r = __builtin_amdgcn_rcpf(1.f + e);
;     const bool val = FULL ? true : (kb + 8 * quad + idx < t);
;     om[idx] = val ? r : 1.f;
;     beta[idx] = val ? e * r : 0.f;
;     prod *= om[idx];
;   }
;   const float a1 = __shfl_xor(prod, 16), a2 = __shfl_xor(prod, 32), a3 = __shfl_xor(a1, 32);
;   const float higher = ((quad ^ 1) > quad ? a1 : 1.f) * ((quad ^ 2) > quad ? a2 : 1.f) * ((quad ^ 3) > quad ? a3 : 1.f);
;   float q = __builtin_amdgcn_exp2f(carry) * higher;
;   float wv[8];
; #pragma unroll
;     ...
;   carry += __builtin_amdgcn_logf((prod * a1) * (a2 * a3));
;   const bf16x8 pf = mk8((u32x4){pk2(wv[0], wv[1]), pk2(wv[2], wv[3]), pk2(wv[4], wv[5]), pk2(wv[6], wv[7])});
; #pragma unroll
;   for (int dt = 0; dt < 4; ++dt) o[dt] = MFMA16(f.v[dt], pf, o[dt]);
; }
	v_cndmask_b32_e64 v186, 1.0, v150, s[8:9]
	s_nop 0
	v_mul_f32_e32 v120, 0x3e38aa3b, v120
	v_min_f32_e32 v120, 0x42700000, v120
	v_add_f32_e32 v150, 1.0, v149
	v_rcp_f32_e32 v150, v150
	v_mfma_f32_16x16x32_bf16 v[116:119], v[128:131], v[36:39], 0
	v_exp_f32_e32 v120, v120
	v_cmp_lt_i32_e64 s[8:9], v163, v156
	v_mul_f32_e32 v148, v186, v148
	v_mul_f32_e32 v149, v149, v150
	v_cndmask_b32_e64 v188, 1.0, v150, s[8:9]
	v_cndmask_b32_e64 v189, 0, v149, s[8:9]
	v_mul_f32_e32 v149, v188, v148
	v_mul_f32_e32 v121, 0x3e38aa3b, v121
	v_mfma_f32_16x16x32_bf16 v[116:119], v[124:127], v[40:43], v[116:119]
	v_add_f32_e32 v124, 1.0, v120
	v_min_f32_e32 v121, 0x42700000, v121
	v_rcp_f32_e32 v124, v124
	v_exp_f32_e32 v121, v121
	v_mul_f32_e32 v120, v120, v124
	v_mul_f32_e32 v122, 0x3e38aa3b, v122
	v_cmp_lt_i32_e64 s[8:9], v172, v152
	v_min_f32_e32 v122, 0x42700000, v122
	v_exp_f32_e32 v122, v122
	v_cndmask_b32_e64 v125, 1.0, v124, s[8:9]
	v_add_f32_e32 v124, 1.0, v121
	v_rcp_f32_e32 v124, v124
	v_cndmask_b32_e64 v120, 0, v120, s[8:9]
	v_cmp_lt_i32_e64 s[8:9], v175, v152
	v_mul_f32_e32 v123, 0x3e38aa3b, v123
	v_mul_f32_e32 v121, v121, v124
	v_cndmask_b32_e64 v126, 1.0, v124, s[8:9]
	v_mul_f32_e32 v124, v125, v126
	v_add_f32_e32 v125, 1.0, v122
	v_min_f32_e32 v123, 0x42700000, v123
	v_rcp_f32_e32 v125, v125
	v_exp_f32_e32 v123, v123
	v_cndmask_b32_e64 v121, 0, v121, s[8:9]
	v_cmp_lt_i32_e64 s[8:9], v177, v152
	v_mul_f32_e32 v116, 0x3e38aa3b, v116
	v_mul_f32_e32 v122, v122, v125
	v_cndmask_b32_e64 v127, 1.0, v125, s[8:9]
	v_add_f32_e32 v125, 1.0, v123
	v_min_f32_e32 v116, 0x42700000, v116
	v_rcp_f32_e32 v125, v125
	v_exp_f32_e32 v116, v116
	v_cndmask_b32_e64 v122, 0, v122, s[8:9]
	v_cmp_lt_i32_e64 s[8:9], v179, v152
	v_mul_f32_e32 v123, v123, v125
	v_mul_f32_e32 v117, 0x3e38aa3b, v117
	v_cndmask_b32_e64 v128, 1.0, v125, s[8:9]
	v_add_f32_e32 v125, 1.0, v116
	v_rcp_f32_e32 v125, v125
	v_min_f32_e32 v117, 0x42700000, v117
	v_exp_f32_e32 v117, v117
	v_mul_f32_e32 v124, v127, v124
	v_cndmask_b32_e64 v123, 0, v123, s[8:9]
	v_cmp_lt_i32_e64 s[8:9], v181, v152
	v_mul_f32_e32 v124, v128, v124
	v_mul_f32_e32 v116, v116, v125
	v_cndmask_b32_e64 v129, 1.0, v125, s[8:9]
	v_cndmask_b32_e64 v125, 0, v116, s[8:9]
	v_mul_f32_e32 v116, v129, v124
	v_add_f32_e32 v124, 1.0, v117
	v_rcp_f32_e32 v124, v124
	v_cmp_lt_i32_e64 s[8:9], v183, v152
	ds_bpermute_b32 v151, v250, v149
	v_mul_f32_e32 v117, v117, v124
	v_cndmask_b32_e64 v130, 1.0, v124, s[8:9]
	v_cndmask_b32_e64 v124, 0, v117, s[8:9]
	v_mul_f32_e32 v117, 0x3e38aa3b, v118
	v_min_f32_e32 v117, 0x42700000, v117
	v_exp_f32_e32 v117, v117
	ds_bpermute_b32 v148, v251, v149
	s_waitcnt lgkmcnt(1)
	ds_bpermute_b32 v150, v251, v151
	v_cmp_lt_i32_e64 s[8:9], v185, v152
	v_add_f32_e32 v118, 1.0, v117
	v_rcp_f32_e32 v118, v118
	s_waitcnt lgkmcnt(1)
	v_cndmask_b32_e64 v192, 1.0, v148, s[44:45]
	s_waitcnt lgkmcnt(0)
	v_pk_mul_f32 v[148:149], v[148:149], v[150:151]
	v_cndmask_b32_e32 v193, 1.0, v151, vcc
	v_mul_f32_e32 v148, v148, v149
	v_mul_f32_e32 v117, v117, v118
	v_log_f32_e32 v149, v148
	v_cndmask_b32_e64 v148, 0, v117, s[8:9]
	v_mul_f32_e32 v117, 0x3e38aa3b, v119
	v_min_f32_e32 v117, 0x42700000, v117
	v_exp_f32_e32 v117, v117
	v_cndmask_b32_e64 v131, 1.0, v118, s[8:9]
	v_mul_f32_e32 v116, v130, v116
	v_cmp_lt_i32_e64 s[8:9], v163, v152
	v_add_f32_e32 v118, 1.0, v117
	v_rcp_f32_e32 v118, v118
	v_mul_f32_e32 v192, v193, v192
	v_cndmask_b32_e64 v193, 1.0, v150, s[46:47]
	v_mul_f32_e32 v116, v131, v116
	v_cndmask_b32_e64 v150, 1.0, v118, s[8:9]
	v_mul_f32_e32 v117, v117, v118
	v_mul_f32_e32 v192, v192, v193
	v_cndmask_b32_e64 v151, 0, v117, s[8:9]
	v_mul_f32_e32 v117, v150, v116
	v_mul_f32_e32 v162, v162, v192
	ds_bpermute_b32 v119, v250, v117
	v_mul_f32_e32 v189, v162, v189
	v_mul_f32_e32 v162, v188, v162
	v_mul_f32_e32 v187, v187, v162
	v_mul_f32_e32 v162, v186, v162
	v_mul_f32_e32 v173, v173, v162
	v_mul_f32_e32 v162, v184, v162
	v_mul_f32_e32 v174, v174, v162
	v_mul_f32_e32 v162, v182, v162
	ds_bpermute_b32 v116, v251, v117
	v_mul_f32_e32 v171, v171, v162
	v_mul_f32_e32 v162, v180, v162
	s_waitcnt lgkmcnt(1)
	ds_bpermute_b32 v118, v251, v119
	v_mul_f32_e32 v170, v170, v162
	v_mul_f32_e32 v162, v178, v162
	v_mul_f32_e32 v169, v169, v162
	v_mul_f32_e32 v162, v176, v162
	v_mul_f32_e32 v162, v168, v162
	v_cvt_pk_bf16_f32 v168, v162, v169
	s_waitcnt lgkmcnt(1)
	v_cndmask_b32_e64 v162, 1.0, v116, s[44:45]
	v_cndmask_b32_e32 v163, 1.0, v119, vcc
	v_mul_f32_e32 v162, v163, v162
	s_waitcnt lgkmcnt(0)
	v_cndmask_b32_e64 v163, 1.0, v118, s[46:47]
	v_mul_f32_e32 v162, v162, v163
	v_mul_f32_e32 v0, v0, v162
	v_mul_f32_e32 v151, v0, v151
	v_mul_f32_e32 v0, v0, v150
	v_mul_f32_e32 v150, v0, v148
	v_mul_f32_e32 v0, v131, v0
	v_mul_f32_e32 v124, v124, v0
	v_mul_f32_e32 v0, v130, v0
	v_mul_f32_e32 v125, v125, v0
	v_mul_f32_e32 v0, v129, v0
	v_mul_f32_e32 v123, v123, v0
	v_mul_f32_e32 v0, v128, v0
	v_mul_f32_e32 v122, v122, v0
	v_mul_f32_e32 v0, v127, v0
	v_mul_f32_e32 v121, v121, v0
	v_mul_f32_e32 v0, v126, v0
	v_pk_mul_f32 v[116:117], v[116:117], v[118:119]
	v_mul_f32_e32 v0, v120, v0
	v_mul_f32_e32 v116, v116, v117
	v_cvt_pk_bf16_f32 v169, v170, v171
	v_cvt_pk_bf16_f32 v170, v174, v173
	v_cvt_pk_bf16_f32 v171, v187, v189
	v_log_f32_e32 v148, v116
	v_cvt_pk_bf16_f32 v116, v0, v121
	v_cvt_pk_bf16_f32 v117, v122, v123
	v_cvt_pk_bf16_f32 v118, v125, v124
	v_cvt_pk_bf16_f32 v119, v150, v151
	s_waitcnt vmcnt(19)
	v_mfma_f32_16x16x32_bf16 v[48:51], v[80:83], v[168:171], v[48:51]
	s_waitcnt vmcnt(18)
	v_mfma_f32_16x16x32_bf16 v[44:47], v[76:79], v[168:171], v[44:47]
	s_waitcnt vmcnt(17)
	v_mfma_f32_16x16x32_bf16 v[24:27], v[64:67], v[168:171], v[24:27]
	s_waitcnt vmcnt(16)
	v_mfma_f32_16x16x32_bf16 v[20:23], v[56:59], v[168:171], v[20:23]
	v_mfma_f32_16x16x32_bf16 v[16:19], v[80:83], v[116:119], v[16:19]
	v_mfma_f32_16x16x32_bf16 v[12:15], v[76:79], v[116:119], v[12:15]
	v_mfma_f32_16x16x32_bf16 v[8:11], v[64:67], v[116:119], v[8:11]
	v_mfma_f32_16x16x32_bf16 v[4:7], v[56:59], v[116:119], v[4:7]
; #define MFMA16(a, b, c) __builtin_amdgcn_mfma_f32_16x16x32_bf16((a), (b), (c), 0, 0, 0)
; DI unsigned pk2(float lo, float hi) { f32x2 v = {lo, hi}; bf16x2_t b = __builtin_convertvector(v, bf16x2_t); return __builtin_bit_cast(unsigned, b); }
; #define SB_STEP(F, KB) (((KB) + 32 <= t0) ? (sb_chunk<true>(F, KB, tA, quad, qa, oa, ca), sb_chunk<true>(F, KB, tB, quad, qb, ob, cb)) : (sb_chunk<false>(F, KB, tA, quad, qa, oa, ca), sb_chunk<false>(F, KB, tB, quad, qb, ob, cb)), __all(ca < -160.f && cb < -160.f))
; template <bool FULL>
; DI void sb_chunk(const SbFrag& f, int kb, int t, int quad, const bf16x8 (&qf)[2], f32x4 (&o)[4], float& carry) {
;   f32x4 s[2];
; #pragma unroll
;   for (int a = 0; a < 2; ++a) {
;     s[a] = MFMA16(f.k[a][0], qf[0], ((f32x4){0.f, 0.f, 0.f, 0.f}));
;     s[a] = MFMA16(f.k[a][1], qf[1], s[a]);
;   }
;   float beta[8], om[8];
;   float prod = 1.f;
; #pragma unroll
;   for (int idx = 0; idx < 8; ++idx) {
;     const float z2 = fminf(s[idx >> 2][idx & 3] * (0.125f * 1.44269504089f), 60.f);
;     const float e = __builtin_amdgcn_exp2f(z2);
;     const float r = __builtin_amdgcn_rcpf(1.f + e);
;     const bool val = FULL ? true : (kb + 8 * quad + idx < t);
;     om[idx] = val ? r : 1.f;
;     beta[idx] = val ? e * r : 0.f;
;     prod *= om[idx];
;   }
;   const float a1 = __shfl_xor(prod, 16), a2 = __shfl_xor(prod, 32), a3 = __shfl_xor(a1, 32);
;   const float higher = ((quad ^ 1) > quad ? a1 : 1.f) * ((quad ^ 2) > quad ? a2 : 1.f) * ((quad ^ 3) > quad ? a3 : 1.f);
;   float q = __builtin_amdgcn_exp2f(carry) * higher;
;   float wv[8];
; #pragma unroll
;     ...
;   carry += __builtin_amdgcn_logf((prod * a1) * (a2 * a3));
;   const bf16x8 pf = mk8((u32x4){pk2(wv[0], wv[1]), pk2(wv[2], wv[3]), pk2(wv[4], wv[5]), pk2(wv[6], wv[7])});
; #pragma unroll
;   for (int dt = 0; dt < 4; ++dt) o[dt] = MFMA16(f.v[dt], pf, o[dt]);
; }
; DI void sb_attn_wave(const Params& p, int b, int h, int t0, bf16_t* ybase) {
;     ...
;     if (SB_STEP(f1, kb - 32) || kb < 64) break;
;     sb_load(f1, kp0, vp0, max(kb - 128, 0));
;     if (SB_STEP(f2, kb - 64) || kb < 96) break;
.LBB0_565:
	s_or_b64 exec, exec, s[10:11]
	v_pk_add_f32 v[2:3], v[2:3], v[148:149]
	s_nop 0
	v_cmp_gt_f32_e64 s[8:9], s31, v3
	v_cmp_gt_f32_e64 s[10:11], s31, v2
	s_and_b64 s[8:9], s[8:9], s[10:11]
	v_cndmask_b32_e64 v0, 0, 1, s[8:9]
	v_cmp_ne_u32_e64 s[8:9], 0, v0
	s_cmp_lg_u64 s[8:9], exec
	s_cselect_b64 s[10:11], -1, 0
	v_cmp_lt_u32_e64 s[8:9], 63, v167
	s_and_b64 s[10:11], s[8:9], s[10:11]
	s_mov_b64 s[8:9], -1
	s_and_saveexec_b64 s[14:15], s[10:11]
	s_cbranch_execz .LBB0_554
	s_movk_i32 s8, 0x80
	v_sub_u32_e64 v0, v167, s8 clamp
	s_waitcnt vmcnt(17)
	v_max_u32_e32 v64, 0x80, v167
	s_waitcnt vmcnt(16)
	v_lshlrev_b64 v[56:57], 7, v[0:1]
	v_lshl_add_u64 v[58:59], v[158:159], 0, v[56:57]
	v_add_u32_e32 v0, 0xffffff84, v64
	global_load_dwordx4 v[120:123], v[58:59], off
	global_load_dwordx4 v[116:119], v[58:59], off offset:64
	v_lshlrev_b64 v[58:59], 7, v[0:1]
	v_lshl_add_u64 v[58:59], v[158:159], 0, v[58:59]
	v_lshl_add_u64 v[56:57], v[160:161], 0, v[56:57]
	global_load_dwordx4 v[128:131], v[58:59], off
	global_load_dwordx4 v[124:127], v[58:59], off offset:64
	global_load_dwordx4 v[80:83], v[56:57], off
	global_load_dwordx4 v[76:79], v[56:57], off offset:1024
	global_load_dwordx4 v[64:67], v[56:57], off offset:2048
	s_nop 0
	global_load_dwordx4 v[56:59], v[56:57], off offset:3072
	v_exp_f32_e32 v162, v3
	v_exp_f32_e32 v0, v2
	v_add_u32_e32 v148, 64, v166
	v_cmp_le_i32_e64 s[8:9], v148, v154
	s_and_saveexec_b64 s[10:11], s[8:9]
	s_xor_b64 s[10:11], exec, s[10:11]
	s_cbranch_execz .LBB0_568
	s_waitcnt vmcnt(23)
	v_mfma_f32_16x16x32_bf16 v[148:151], v[136:139], v[28:31], 0
	s_waitcnt vmcnt(21)
	v_mfma_f32_16x16x32_bf16 v[168:171], v[144:147], v[28:31], 0
	v_mfma_f32_16x16x32_bf16 v[148:151], v[140:143], v[32:35], v[148:151]
	s_waitcnt vmcnt(20)
	v_mfma_f32_16x16x32_bf16 v[168:171], v[132:135], v[32:35], v[168:171]
	v_mfma_f32_16x16x32_bf16 v[136:139], v[136:139], v[36:39], 0
	s_nop 4
	v_mul_f32_e32 v148, 0x3e38aa3b, v148
	v_mul_f32_e32 v150, 0x3e38aa3b, v150
	v_min_f32_e32 v148, 0x42700000, v148
	v_exp_f32_e32 v148, v148
	v_min_f32_e32 v150, 0x42700000, v150
	v_mul_f32_e32 v151, 0x3e38aa3b, v151
	v_exp_f32_e32 v150, v150
	v_min_f32_e32 v151, 0x42700000, v151
	v_mul_f32_e32 v168, 0x3e38aa3b, v168
	v_exp_f32_e32 v151, v151
	v_min_f32_e32 v168, 0x42700000, v168
	v_mul_f32_e32 v169, 0x3e38aa3b, v169
	v_exp_f32_e32 v168, v168
	v_min_f32_e32 v169, 0x42700000, v169
	v_mul_f32_e32 v170, 0x3e38aa3b, v170
	v_add_f32_e32 v163, 1.0, v148
	v_exp_f32_e32 v169, v169
	v_min_f32_e32 v170, 0x42700000, v170
	v_mul_f32_e32 v171, 0x3e38aa3b, v171
	v_rcp_f32_e32 v172, v163
	v_add_f32_e32 v163, 1.0, v150
	v_exp_f32_e32 v170, v170
	v_min_f32_e32 v171, 0x42700000, v171
	v_mul_f32_e32 v149, 0x3e38aa3b, v149
	v_rcp_f32_e32 v174, v163
	v_add_f32_e32 v163, 1.0, v151
	v_exp_f32_e32 v171, v171
	v_min_f32_e32 v149, 0x42700000, v149
	v_rcp_f32_e32 v175, v163
	v_add_f32_e32 v163, 1.0, v168
	v_exp_f32_e32 v149, v149
	v_rcp_f32_e32 v176, v163
	v_add_f32_e32 v163, 1.0, v169
	v_rcp_f32_e32 v177, v163
	v_add_f32_e32 v163, 1.0, v170
	v_rcp_f32_e32 v178, v163
	v_add_f32_e32 v163, 1.0, v171
	v_rcp_f32_e32 v179, v163
	v_add_f32_e32 v173, 1.0, v149
	v_rcp_f32_e32 v173, v173
	v_mfma_f32_16x16x32_bf16 v[136:139], v[140:143], v[40:43], v[136:139]
	v_mfma_f32_16x16x32_bf16 v[140:143], v[144:147], v[36:39], 0
	v_mul_f32_e64 v148, v148, v172
	v_mul_f32_e64 v149, v149, v173
	v_mul_f32_e32 v163, v172, v173
	v_mul_f32_e32 v163, v174, v163
	v_mul_f32_e32 v163, v175, v163
	v_mul_f32_e32 v163, v176, v163
	v_mul_f32_e32 v163, v177, v163
	v_mul_f32_e32 v163, v178, v163
	v_mul_f32_e32 v181, v179, v163
	ds_bpermute_b32 v183, v250, v181
	ds_bpermute_b32 v180, v251, v181
	v_mfma_f32_16x16x32_bf16 v[132:135], v[132:135], v[40:43], v[140:143]
	v_mul_f32_e32 v136, 0x3e38aa3b, v136
	v_mul_f32_e32 v137, 0x3e38aa3b, v137
	s_waitcnt lgkmcnt(1)
	ds_bpermute_b32 v182, v251, v183
	s_waitcnt lgkmcnt(1)
	v_cndmask_b32_e64 v163, 1.0, v180, s[44:45]
	v_cndmask_b32_e32 v172, 1.0, v183, vcc
	v_mul_f32_e32 v163, v172, v163
	v_min_f32_e32 v136, 0x42700000, v136
	s_waitcnt lgkmcnt(0)
	v_cndmask_b32_e64 v172, 1.0, v182, s[46:47]
	v_mul_f32_e32 v163, v163, v172
	v_mul_f32_e32 v163, v162, v163
	v_min_f32_e32 v137, 0x42700000, v137
	v_mul_f32_e32 v138, 0x3e38aa3b, v138
	v_pk_mul_f32 v[170:171], v[170:171], v[178:179]
	v_mul_f32_e32 v162, v179, v163
	v_exp_f32_e32 v136, v136
	v_exp_f32_e32 v137, v137
	v_min_f32_e32 v138, 0x42700000, v138
	v_mul_f32_e32 v139, 0x3e38aa3b, v139
	v_pk_mul_f32 v[170:171], v[170:171], v[162:163]
	v_mul_f32_e32 v163, v178, v162
	v_exp_f32_e32 v138, v138
	v_min_f32_e32 v139, 0x42700000, v139
	v_mul_f32_e32 v132, 0x3e38aa3b, v132
	v_pk_mul_f32 v[168:169], v[168:169], v[176:177]
	v_mul_f32_e32 v162, v177, v163
	v_exp_f32_e32 v139, v139
	v_min_f32_e32 v132, 0x42700000, v132
	v_mul_f32_e32 v133, 0x3e38aa3b, v133
	v_pk_mul_f32 v[168:169], v[168:169], v[162:163]
	v_mul_f32_e32 v163, v176, v162
	v_exp_f32_e32 v132, v132
	v_min_f32_e32 v133, 0x42700000, v133
	v_mul_f32_e32 v134, 0x3e38aa3b, v134
	v_pk_mul_f32 v[150:151], v[150:151], v[174:175]
	v_mul_f32_e32 v162, v175, v163
	v_add_f32_e32 v140, 1.0, v136
	v_add_f32_e32 v141, 1.0, v137
	v_exp_f32_e32 v133, v133
	v_min_f32_e32 v134, 0x42700000, v134
	v_mul_f32_e32 v135, 0x3e38aa3b, v135
	v_pk_mul_f32 v[150:151], v[150:151], v[162:163]
	v_mul_f32_e32 v163, v174, v162
	v_rcp_f32_e32 v140, v140
	v_rcp_f32_e32 v141, v141
	v_add_f32_e32 v142, 1.0, v138
	v_exp_f32_e32 v134, v134
	v_min_f32_e32 v135, 0x42700000, v135
	v_mul_f32_e32 v162, v173, v163
	v_rcp_f32_e32 v142, v142
	v_add_f32_e32 v143, 1.0, v139
	v_exp_f32_e32 v135, v135
	v_pk_mul_f32 v[148:149], v[148:149], v[162:163]
	v_rcp_f32_e32 v143, v143
	v_add_f32_e32 v144, 1.0, v132
	v_cvt_pk_bf16_f32 v148, v148, v149
	v_cvt_pk_bf16_f32 v149, v150, v151
	v_cvt_pk_bf16_f32 v150, v168, v169
	v_cvt_pk_bf16_f32 v151, v170, v171
	v_rcp_f32_e32 v144, v144
	v_add_f32_e32 v145, 1.0, v133
	s_waitcnt vmcnt(19)
; #define MFMA16(a, b, c) __builtin_amdgcn_mfma_f32_16x16x32_bf16((a), (b), (c), 0, 0, 0)
; DI unsigned pk2(float lo, float hi) { f32x2 v = {lo, hi}; bf16x2_t b = __builtin_convertvector(v, bf16x2_t); return __builtin_bit_cast(unsigned, b); }
; template <bool FULL>
; DI void sb_chunk(const SbFrag& f, int kb, int t, int quad, const bf16x8 (&qf)[2], f32x4 (&o)[4], float& carry) {
;   f32x4 s[2];
; #pragma unroll
;   for (int a = 0; a < 2; ++a) {
;     s[a] = MFMA16(f.k[a][0], qf[0], ((f32x4){0.f, 0.f, 0.f, 0.f}));
;     s[a] = MFMA16(f.k[a][1], qf[1], s[a]);
;   }
;   float beta[8], om[8];
;   float prod = 1.f;
; #pragma unroll
;   for (int idx = 0; idx < 8; ++idx) {
;     const float z2 = fminf(s[idx >> 2][idx & 3] * (0.125f * 1.44269504089f), 60.f);
;     const float e = __builtin_amdgcn_exp2f(z2);
;     const float r = __builtin_amdgcn_rcpf(1.f + e);
;     const bool val = FULL ? true : (kb + 8 * quad + idx < t);
;     om[idx] = val ? r : 1.f;
;     beta[idx] = val ? e * r : 0.f;
;     prod *= om[idx];
;   }
;   const float a1 = __shfl_xor(prod, 16), a2 = __shfl_xor(prod, 32), a3 = __shfl_xor(a1, 32);
;   const float higher = ((quad ^ 1) > quad ? a1 : 1.f) * ((quad ^ 2) > quad ? a2 : 1.f) * ((quad ^ 3) > quad ? a3 : 1.f);
;   float q = __builtin_amdgcn_exp2f(carry) * higher;
;   float wv[8];
; #pragma unroll
;     ...
;   carry += __builtin_amdgcn_logf((prod * a1) * (a2 * a3));
;   const bf16x8 pf = mk8((u32x4){pk2(wv[0], wv[1]), pk2(wv[2], wv[3]), pk2(wv[4], wv[5]), pk2(wv[6], wv[7])});
; #pragma unroll
;   for (int dt = 0; dt < 4; ++dt) o[dt] = MFMA16(f.v[dt], pf, o[dt]);
; }
	v_mfma_f32_16x16x32_bf16 v[48:51], v[92:95], v[148:151], v[48:51]
	v_rcp_f32_e32 v145, v145
	v_add_f32_e32 v146, 1.0, v134
	v_rcp_f32_e32 v146, v146
	s_waitcnt vmcnt(18)
	v_mfma_f32_16x16x32_bf16 v[44:47], v[96:99], v[148:151], v[44:47]
	v_add_f32_e32 v147, 1.0, v135
	v_rcp_f32_e32 v147, v147
	v_pk_mul_f32 v[136:137], v[136:137], v[140:141]
	s_waitcnt vmcnt(17)
	v_mfma_f32_16x16x32_bf16 v[24:27], v[88:91], v[148:151], v[24:27]
	v_mul_f32_e64 v132, v132, v144
	v_mul_f32_e64 v133, v133, v145
	v_pk_mul_f32 v[134:135], v[134:135], v[146:147]
	v_pk_mul_f32 v[138:139], v[138:139], v[142:143]
	s_waitcnt vmcnt(16)
	v_mfma_f32_16x16x32_bf16 v[20:23], v[84:87], v[148:151], v[20:23]
	v_mul_f32_e32 v148, v140, v141
	v_mul_f32_e32 v148, v142, v148
	v_mul_f32_e32 v148, v143, v148
	v_mul_f32_e32 v148, v144, v148
	v_mul_f32_e32 v148, v145, v148
	v_mul_f32_e32 v148, v146, v148
	v_mul_f32_e32 v151, v147, v148
	ds_bpermute_b32 v163, v250, v151
	ds_bpermute_b32 v150, v251, v151
	s_waitcnt lgkmcnt(1)
	ds_bpermute_b32 v162, v251, v163
	s_waitcnt lgkmcnt(1)
	v_cndmask_b32_e64 v140, 1.0, v150, s[44:45]
	v_cndmask_b32_e32 v148, 1.0, v163, vcc
	v_mul_f32_e32 v140, v148, v140
	s_waitcnt lgkmcnt(0)
	v_cndmask_b32_e64 v148, 1.0, v162, s[46:47]
	v_mul_f32_e32 v140, v140, v148
	v_mul_f32_e32 v149, v0, v140
	v_mul_f32_e32 v148, v149, v147
	v_pk_mul_f32 v[168:169], v[148:149], v[134:135]
	v_mul_f32_e32 v135, v146, v148
	v_mul_f32_e32 v134, v145, v135
	v_pk_mul_f32 v[146:147], v[132:133], v[134:135]
	v_mul_f32_e32 v133, v144, v134
	v_mul_f32_e32 v132, v143, v133
	v_pk_mul_f32 v[134:135], v[138:139], v[132:133]
	v_mul_f32_e32 v133, v142, v132
	v_mul_f32_e32 v132, v141, v133
	v_pk_mul_f32 v[132:133], v[136:137], v[132:133]
	s_nop 0
	v_cvt_pk_bf16_f32 v132, v132, v133
	v_cvt_pk_bf16_f32 v133, v134, v135
	v_cvt_pk_bf16_f32 v134, v146, v147
	v_cvt_pk_bf16_f32 v135, v168, v169
	s_nop 1
	v_mfma_f32_16x16x32_bf16 v[16:19], v[92:95], v[132:135], v[16:19]
	v_mul_f32_e64 v92, v180, v182
	v_mul_f32_e64 v93, v181, v183
	v_mul_f32_e32 v0, v92, v93
	v_mfma_f32_16x16x32_bf16 v[8:11], v[88:91], v[132:135], v[8:11]
	v_mul_f32_e64 v88, v150, v162
	v_mul_f32_e64 v89, v151, v163
	v_log_f32_e32 v149, v0
	v_mul_f32_e32 v0, v88, v89
	v_mfma_f32_16x16x32_bf16 v[12:15], v[96:99], v[132:135], v[12:15]
	v_log_f32_e32 v148, v0
	v_mfma_f32_16x16x32_bf16 v[4:7], v[84:87], v[132:135], v[4:7]
.LBB0_568:
	s_andn2_saveexec_b64 s[10:11], s[10:11]
	s_cbranch_execz .LBB0_553
	s_waitcnt vmcnt(23)
	v_mfma_f32_16x16x32_bf16 v[148:151], v[136:139], v[28:31], 0
	v_add_u32_e32 v163, v155, v166
	v_add_u32_e32 v172, 32, v163
	v_cmp_lt_i32_e64 s[8:9], v172, v156
	s_waitcnt vmcnt(22)
	v_mfma_f32_16x16x32_bf16 v[168:171], v[140:143], v[32:35], v[148:151]
	v_add_u32_e32 v175, 33, v163
	v_add_u32_e32 v177, 34, v163
	v_add_u32_e32 v179, 35, v163
	s_waitcnt vmcnt(21)
	v_mfma_f32_16x16x32_bf16 v[148:151], v[144:147], v[28:31], 0
	v_add_u32_e32 v181, 36, v163
	s_nop 1
	v_mul_f32_e32 v168, 0x3e38aa3b, v168
	v_min_f32_e32 v168, 0x42700000, v168
	v_exp_f32_e32 v168, v168
	v_mul_f32_e32 v169, 0x3e38aa3b, v169
	v_min_f32_e32 v169, 0x42700000, v169
	v_exp_f32_e32 v169, v169
	v_add_f32_e32 v173, 1.0, v168
	v_rcp_f32_e32 v173, v173
	v_mul_f32_e32 v170, 0x3e38aa3b, v170
	v_min_f32_e32 v170, 0x42700000, v170
	v_exp_f32_e32 v170, v170
	v_cndmask_b32_e64 v174, 1.0, v173, s[8:9]
	v_mul_f32_e32 v168, v168, v173
	v_add_f32_e32 v173, 1.0, v169
	v_rcp_f32_e32 v173, v173
	v_cndmask_b32_e64 v168, 0, v168, s[8:9]
	v_cmp_lt_i32_e64 s[8:9], v175, v156
	v_mul_f32_e32 v171, 0x3e38aa3b, v171
	s_waitcnt vmcnt(20)
	v_mfma_f32_16x16x32_bf16 v[148:151], v[132:135], v[32:35], v[148:151]
	v_cndmask_b32_e64 v176, 1.0, v173, s[8:9]
	v_mul_f32_e32 v169, v169, v173
	v_mul_f32_e32 v173, v174, v176
	v_add_f32_e32 v174, 1.0, v170
	v_min_f32_e32 v171, 0x42700000, v171
	v_rcp_f32_e32 v174, v174
	v_exp_f32_e32 v171, v171
	v_cndmask_b32_e64 v169, 0, v169, s[8:9]
	v_cmp_lt_i32_e64 s[8:9], v177, v156
	v_mul_f32_e32 v148, 0x3e38aa3b, v148
	v_mul_f32_e32 v170, v170, v174
	v_cndmask_b32_e64 v178, 1.0, v174, s[8:9]
	v_add_f32_e32 v174, 1.0, v171
	v_min_f32_e32 v148, 0x42700000, v148
	v_rcp_f32_e32 v174, v174
	v_exp_f32_e32 v148, v148
	v_cndmask_b32_e64 v170, 0, v170, s[8:9]
	v_cmp_lt_i32_e64 s[8:9], v179, v156
	v_mul_f32_e32 v171, v171, v174
	v_mul_f32_e32 v149, 0x3e38aa3b, v149
	v_cndmask_b32_e64 v180, 1.0, v174, s[8:9]
	v_add_f32_e32 v174, 1.0, v148
	v_rcp_f32_e32 v174, v174
	v_min_f32_e32 v149, 0x42700000, v149
	v_exp_f32_e32 v149, v149
	v_mul_f32_e32 v173, v178, v173
	v_cndmask_b32_e64 v171, 0, v171, s[8:9]
	v_cmp_lt_i32_e64 s[8:9], v181, v156
	v_mul_f32_e32 v173, v180, v173
	v_mul_f32_e32 v148, v148, v174
	v_cndmask_b32_e64 v182, 1.0, v174, s[8:9]
	v_cndmask_b32_e64 v174, 0, v148, s[8:9]
	v_mul_f32_e32 v148, v182, v173
	v_add_f32_e32 v173, 1.0, v149
	v_rcp_f32_e32 v173, v173
	v_add_u32_e32 v183, 37, v163
	v_cmp_lt_i32_e64 s[8:9], v183, v156
	v_add_u32_e32 v185, 38, v163
	v_mul_f32_e32 v149, v149, v173
	v_cndmask_b32_e64 v184, 1.0, v173, s[8:9]
	v_cndmask_b32_e64 v173, 0, v149, s[8:9]
	v_mul_f32_e32 v149, 0x3e38aa3b, v150
	v_min_f32_e32 v149, 0x42700000, v149
	v_exp_f32_e32 v149, v149
	v_cmp_lt_i32_e64 s[8:9], v185, v156
	v_mfma_f32_16x16x32_bf16 v[136:139], v[136:139], v[36:39], 0
	v_add_u32_e32 v163, 39, v163
	v_add_f32_e32 v150, 1.0, v149
	v_rcp_f32_e32 v150, v150
	v_mfma_f32_16x16x32_bf16 v[136:139], v[140:143], v[40:43], v[136:139]
	v_mul_f32_e32 v148, v184, v148
	v_mul_f32_e32 v149, v149, v150
	v_cndmask_b32_e64 v187, 0, v149, s[8:9]
	v_mul_f32_e32 v149, 0x3e38aa3b, v151
	v_min_f32_e32 v149, 0x42700000, v149
	v_exp_f32_e32 v149, v149
	v_cndmask_b32_e64 v186, 1.0, v150, s[8:9]
; #define MFMA16(a, b, c) __builtin_amdgcn_mfma_f32_16x16x32_bf16((a), (b), (c), 0, 0, 0)
; DI unsigned pk2(float lo, float hi) { f32x2 v = {lo, hi}; bf16x2_t b = __builtin_convertvector(v, bf16x2_t); return __builtin_bit_cast(unsigned, b); }
; #define SB_STEP(F, KB) (((KB) + 32 <= t0) ? (sb_chunk<true>(F, KB, tA, quad, qa, oa, ca), sb_chunk<true>(F, KB, tB, quad, qb, ob, cb)) : (sb_chunk<false>(F, KB, tA, quad, qa, oa, ca), sb_chunk<false>(F, KB, tB, quad, qb, ob, cb)), __all(ca < -160.f && cb < -160.f))
; template <bool FULL>
; DI void sb_chunk(const SbFrag& f, int kb, int t, int quad, const bf16x8 (&qf)[2], f32x4 (&o)[4], float& carry) {
;   f32x4 s[2];
; #pragma unroll
;   for (int a = 0; a < 2; ++a) {
;     s[a] = MFMA16(f.k[a][0], qf[0], ((f32x4){0.f, 0.f, 0.f, 0.f}));
;     s[a] = MFMA16(f.k[a][1], qf[1], s[a]);
;   }
;   float beta[8], om[8];
;   float prod = 1.f;
; #pragma unroll
;   for (int idx = 0; idx < 8; ++idx) {
;     const float z2 = fminf(s[idx >> 2][idx & 3] * (0.125f * 1.44269504089f), 60.f);
;     const float e = __builtin_amdgcn_exp2f(z2);
;     const float r = __builtin_amdgcn_rcpf(1.f + e);
;     const bool val = FULL ? true : (kb + 8 * quad + idx < t);
;     om[idx] = val ? r : 1.f;
;     beta[idx] = val ? e * r : 0.f;
;     prod *= om[idx];
;   }
;   const float a1 = __shfl_xor(prod, 16), a2 = __shfl_xor(prod, 32), a3 = __shfl_xor(a1, 32);
;   const float higher = ((quad ^ 1) > quad ? a1 : 1.f) * ((quad ^ 2) > quad ? a2 : 1.f) * ((quad ^ 3) > quad ? a3 : 1.f);
;   float q = __builtin_amdgcn_exp2f(carry) * higher;
;   float wv[8];
; #pragma unroll
;     ...
;   carry += __builtin_amdgcn_logf((prod * a1) * (a2 * a3));
;   const bf16x8 pf = mk8((u32x4){pk2(wv[0], wv[1]), pk2(wv[2], wv[3]), pk2(wv[4], wv[5]), pk2(wv[6], wv[7])});
; #pragma unroll
;   for (int dt = 0; dt < 4; ++dt) o[dt] = MFMA16(f.v[dt], pf, o[dt]);
; }
; DI void sb_attn_wave(const Params& p, int b, int h, int t0, bf16_t* ybase) {
;     ...
;     if (SB_STEP(f2, kb - 64) || kb < 96) break;
;     kb -= 96;
	s_nop 0
	v_mul_f32_e32 v136, 0x3e38aa3b, v136
	v_min_f32_e32 v136, 0x42700000, v136
	v_add_f32_e32 v150, 1.0, v149
	v_rcp_f32_e32 v150, v150
	v_mfma_f32_16x16x32_bf16 v[140:143], v[144:147], v[36:39], 0
	v_exp_f32_e32 v136, v136
	v_cmp_lt_i32_e64 s[8:9], v163, v156
	v_mul_f32_e32 v148, v186, v148
	v_mul_f32_e32 v149, v149, v150
	v_cndmask_b32_e64 v188, 1.0, v150, s[8:9]
	v_cndmask_b32_e64 v189, 0, v149, s[8:9]
	v_mul_f32_e32 v149, v188, v148
	v_mul_f32_e32 v137, 0x3e38aa3b, v137
	v_mfma_f32_16x16x32_bf16 v[132:135], v[132:135], v[40:43], v[140:143]
	v_min_f32_e32 v137, 0x42700000, v137
	v_exp_f32_e32 v137, v137
	v_add_f32_e32 v140, 1.0, v136
	v_rcp_f32_e32 v140, v140
	v_mul_f32_e32 v136, v136, v140
	v_mul_f32_e32 v138, 0x3e38aa3b, v138
	v_cmp_lt_i32_e64 s[8:9], v172, v152
	v_min_f32_e32 v138, 0x42700000, v138
	v_exp_f32_e32 v138, v138
	v_cndmask_b32_e64 v141, 1.0, v140, s[8:9]
	v_add_f32_e32 v140, 1.0, v137
	v_rcp_f32_e32 v140, v140
	v_cndmask_b32_e64 v136, 0, v136, s[8:9]
	v_cmp_lt_i32_e64 s[8:9], v175, v152
	v_mul_f32_e32 v139, 0x3e38aa3b, v139
	v_mul_f32_e32 v137, v137, v140
	v_cndmask_b32_e64 v142, 1.0, v140, s[8:9]
	v_mul_f32_e32 v140, v141, v142
	v_add_f32_e32 v141, 1.0, v138
	v_min_f32_e32 v139, 0x42700000, v139
	v_rcp_f32_e32 v141, v141
	v_exp_f32_e32 v139, v139
	v_cndmask_b32_e64 v137, 0, v137, s[8:9]
	v_cmp_lt_i32_e64 s[8:9], v177, v152
	v_mul_f32_e32 v132, 0x3e38aa3b, v132
	v_mul_f32_e32 v138, v138, v141
	v_cndmask_b32_e64 v143, 1.0, v141, s[8:9]
	v_add_f32_e32 v141, 1.0, v139
	v_min_f32_e32 v132, 0x42700000, v132
	v_rcp_f32_e32 v141, v141
	v_exp_f32_e32 v132, v132
	v_cndmask_b32_e64 v138, 0, v138, s[8:9]
	v_cmp_lt_i32_e64 s[8:9], v179, v152
	v_mul_f32_e32 v139, v139, v141
	v_mul_f32_e32 v133, 0x3e38aa3b, v133
	v_cndmask_b32_e64 v144, 1.0, v141, s[8:9]
	v_add_f32_e32 v141, 1.0, v132
	v_rcp_f32_e32 v141, v141
	v_min_f32_e32 v133, 0x42700000, v133
	v_exp_f32_e32 v133, v133
	v_mul_f32_e32 v140, v143, v140
	v_cndmask_b32_e64 v139, 0, v139, s[8:9]
	v_cmp_lt_i32_e64 s[8:9], v181, v152
	v_mul_f32_e32 v140, v144, v140
	v_mul_f32_e32 v132, v132, v141
	v_cndmask_b32_e64 v145, 1.0, v141, s[8:9]
	v_cndmask_b32_e64 v141, 0, v132, s[8:9]
	v_mul_f32_e32 v132, v145, v140
	v_add_f32_e32 v140, 1.0, v133
	v_rcp_f32_e32 v140, v140
	v_cmp_lt_i32_e64 s[8:9], v183, v152
	ds_bpermute_b32 v151, v250, v149
	v_mul_f32_e32 v133, v133, v140
	v_cndmask_b32_e64 v146, 1.0, v140, s[8:9]
	v_cndmask_b32_e64 v140, 0, v133, s[8:9]
	v_mul_f32_e32 v133, 0x3e38aa3b, v134
	v_min_f32_e32 v133, 0x42700000, v133
	v_exp_f32_e32 v133, v133
	ds_bpermute_b32 v148, v251, v149
	s_waitcnt lgkmcnt(1)
	ds_bpermute_b32 v150, v251, v151
	v_cmp_lt_i32_e64 s[8:9], v185, v152
	v_add_f32_e32 v134, 1.0, v133
	v_rcp_f32_e32 v134, v134
	s_waitcnt lgkmcnt(1)
	v_cndmask_b32_e64 v192, 1.0, v148, s[44:45]
	s_waitcnt lgkmcnt(0)
	v_pk_mul_f32 v[148:149], v[148:149], v[150:151]
	v_cndmask_b32_e32 v193, 1.0, v151, vcc
	v_mul_f32_e32 v148, v148, v149
	v_mul_f32_e32 v133, v133, v134
	v_log_f32_e32 v149, v148
	v_cndmask_b32_e64 v148, 0, v133, s[8:9]
	v_mul_f32_e32 v133, 0x3e38aa3b, v135
	v_min_f32_e32 v133, 0x42700000, v133
	v_exp_f32_e32 v133, v133
	v_cndmask_b32_e64 v147, 1.0, v134, s[8:9]
	v_mul_f32_e32 v132, v146, v132
	v_cmp_lt_i32_e64 s[8:9], v163, v152
	v_add_f32_e32 v134, 1.0, v133
	v_rcp_f32_e32 v134, v134
	v_mul_f32_e32 v192, v193, v192
	v_cndmask_b32_e64 v193, 1.0, v150, s[46:47]
	v_mul_f32_e32 v132, v147, v132
	v_cndmask_b32_e64 v150, 1.0, v134, s[8:9]
	v_mul_f32_e32 v133, v133, v134
	v_mul_f32_e32 v192, v192, v193
	v_cndmask_b32_e64 v151, 0, v133, s[8:9]
	v_mul_f32_e32 v133, v150, v132
	v_mul_f32_e32 v162, v162, v192
	ds_bpermute_b32 v135, v250, v133
	v_mul_f32_e32 v189, v162, v189
	v_mul_f32_e32 v162, v188, v162
	v_mul_f32_e32 v187, v187, v162
	v_mul_f32_e32 v162, v186, v162
	v_mul_f32_e32 v173, v173, v162
	v_mul_f32_e32 v162, v184, v162
	v_mul_f32_e32 v174, v174, v162
	v_mul_f32_e32 v162, v182, v162
	ds_bpermute_b32 v132, v251, v133
	v_mul_f32_e32 v171, v171, v162
	v_mul_f32_e32 v162, v180, v162
	s_waitcnt lgkmcnt(1)
	ds_bpermute_b32 v134, v251, v135
	v_mul_f32_e32 v170, v170, v162
	v_mul_f32_e32 v162, v178, v162
	v_mul_f32_e32 v169, v169, v162
	v_mul_f32_e32 v162, v176, v162
	v_mul_f32_e32 v162, v168, v162
	v_cvt_pk_bf16_f32 v168, v162, v169
	s_waitcnt lgkmcnt(1)
	v_cndmask_b32_e64 v162, 1.0, v132, s[44:45]
	v_cndmask_b32_e32 v163, 1.0, v135, vcc
	v_mul_f32_e32 v162, v163, v162
	s_waitcnt lgkmcnt(0)
	v_cndmask_b32_e64 v163, 1.0, v134, s[46:47]
	v_mul_f32_e32 v162, v162, v163
	v_mul_f32_e32 v0, v0, v162
	v_mul_f32_e32 v151, v0, v151
	v_mul_f32_e32 v0, v0, v150
	v_mul_f32_e32 v150, v0, v148
	v_mul_f32_e32 v0, v147, v0
	v_mul_f32_e32 v140, v140, v0
	v_mul_f32_e32 v0, v146, v0
	v_mul_f32_e32 v141, v141, v0
	v_mul_f32_e32 v0, v145, v0
	v_mul_f32_e32 v139, v139, v0
	v_mul_f32_e32 v0, v144, v0
	v_mul_f32_e32 v138, v138, v0
	v_mul_f32_e32 v0, v143, v0
	v_mul_f32_e32 v137, v137, v0
	v_mul_f32_e32 v0, v142, v0
	v_pk_mul_f32 v[132:133], v[132:133], v[134:135]
	v_mul_f32_e32 v0, v136, v0
	v_mul_f32_e32 v132, v132, v133
	v_cvt_pk_bf16_f32 v169, v170, v171
	v_cvt_pk_bf16_f32 v170, v174, v173
	v_cvt_pk_bf16_f32 v171, v187, v189
	v_log_f32_e32 v148, v132
	v_cvt_pk_bf16_f32 v132, v0, v137
	v_cvt_pk_bf16_f32 v133, v138, v139
	v_cvt_pk_bf16_f32 v134, v141, v140
	v_cvt_pk_bf16_f32 v135, v150, v151
	s_waitcnt vmcnt(19)
	v_mfma_f32_16x16x32_bf16 v[48:51], v[92:95], v[168:171], v[48:51]
	s_waitcnt vmcnt(18)
	v_mfma_f32_16x16x32_bf16 v[44:47], v[96:99], v[168:171], v[44:47]
	s_waitcnt vmcnt(17)
	v_mfma_f32_16x16x32_bf16 v[24:27], v[88:91], v[168:171], v[24:27]
	s_waitcnt vmcnt(16)
	v_mfma_f32_16x16x32_bf16 v[20:23], v[84:87], v[168:171], v[20:23]
	v_mfma_f32_16x16x32_bf16 v[16:19], v[92:95], v[132:135], v[16:19]
	v_mfma_f32_16x16x32_bf16 v[12:15], v[96:99], v[132:135], v[12:15]
	v_mfma_f32_16x16x32_bf16 v[8:11], v[88:91], v[132:135], v[8:11]
	v_mfma_f32_16x16x32_bf16 v[4:7], v[84:87], v[132:135], v[4:7]
	s_branch .LBB0_553

; #define MFMA16(a, b, c) __builtin_amdgcn_mfma_f32_16x16x32_bf16((a), (b), (c), 0, 0, 0)
; DI unsigned pk2(float lo, float hi) { f32x2 v = {lo, hi}; bf16x2_t b = __builtin_convertvector(v, bf16x2_t); return __builtin_bit_cast(unsigned, b); }
; template <int MODE>
; DI void nsa_chunk(const KVFrag& f, int kb, int t, bool selbit, const bf16x8 (&qf)[4][2], f32x4 (&O)[4][4], float (&m)[4], float (&l)[4], int quad, bool online) {
;     ...
;   for (int hh = 0; hh < 4; ++hh) {
;     f32x4 s[2];
; #pragma unroll
;     for (int a = 0; a < 2; ++a) { s[a] = MFMA16(f.k[a][0], qf[hh][0], ((f32x4){0.f, 0.f, 0.f, 0.f})); s[a] = MFMA16(f.k[a][1], qf[hh][1], s[a]); }
;     float mn = m[hh];
;     if (online) {
;       float cm = -1e30f;
; #pragma unroll
;       for (int idx = 0; idx < 8; ++idx) if (val[idx]) cm = fmaxf(cm, s[idx >> 2][idx & 3] * SC);
;       cm = fmaxf(cm, __shfl_xor(cm, 16)); cm = fmaxf(cm, __shfl_xor(cm, 32));
;       mn = fmaxf(mn, cm);
;       const float alpha = __builtin_amdgcn_exp2f(m[hh] - mn);
;       m[hh] = mn; l[hh] *= alpha;
; #pragma unroll
;       for (int dt = 0; dt < 4; ++dt) O[hh][dt] = O[hh][dt] * alpha;
;     }
;     float pv[8]; float ps = 0.f;
; #pragma unroll
;     for (int idx = 0; idx < 8; ++idx) { pv[idx] = val[idx] ? __builtin_amdgcn_exp2f(fmaf(s[idx >> 2][idx & 3], SC, -mn)) : 0.f; ps += pv[idx]; }
;     l[hh] += ps;
;     const bf16x8 pf = mk8((u32x4){pk2(pv[0], pv[1]), pk2(pv[2], pv[3]), pk2(pv[4], pv[5]), pk2(pv[6], pv[7])});
; #pragma unroll
;     for (int dt = 0; dt < 4; ++dt) O[hh][dt] = MFMA16(f.v[dt], pf, O[hh][dt]);
;   }
.Lmy_fast_s1:
	s_waitcnt lgkmcnt(4)
	v_mfma_f32_16x16x32_bf16 v[182:185], v[136:139], v[8:11], v[218:221]
	v_mfma_f32_16x16x32_bf16 v[182:185], v[140:143], v[12:15], v[182:185]
	v_mfma_f32_16x16x32_bf16 v[186:189], v[144:147], v[8:11], v[222:225]
	v_mfma_f32_16x16x32_bf16 v[186:189], v[132:135], v[12:15], v[186:189]
	v_mfma_f32_16x16x32_bf16 v[190:193], v[136:139], v[16:19], v[218:221]
	v_mfma_f32_16x16x32_bf16 v[190:193], v[140:143], v[20:23], v[190:193]
	v_mfma_f32_16x16x32_bf16 v[194:197], v[144:147], v[16:19], v[222:225]
	v_mfma_f32_16x16x32_bf16 v[194:197], v[132:135], v[20:23], v[194:197]
	s_waitcnt lgkmcnt(0)
	s_nop 2
	v_pk_fma_f32 v[240:241], v[182:183], s[34:35], v[2:3] op_sel:[0,0,1] op_sel_hi:[1,0,1] neg_lo:[0,0,1] neg_hi:[0,0,1]
	v_pk_fma_f32 v[242:243], v[184:185], s[34:35], v[2:3] op_sel:[0,0,1] op_sel_hi:[1,0,1] neg_lo:[0,0,1] neg_hi:[0,0,1]
	v_pk_fma_f32 v[244:245], v[186:187], s[34:35], v[2:3] op_sel:[0,0,1] op_sel_hi:[1,0,1] neg_lo:[0,0,1] neg_hi:[0,0,1]
	v_pk_fma_f32 v[246:247], v[188:189], s[34:35], v[2:3] op_sel:[0,0,1] op_sel_hi:[1,0,1] neg_lo:[0,0,1] neg_hi:[0,0,1]
	v_exp_f32_e32 v240, v240
	v_exp_f32_e32 v241, v241
	v_mfma_f32_16x16x32_bf16 v[182:185], v[136:139], v[24:27], v[218:221]
	v_exp_f32_e32 v242, v242
	v_exp_f32_e32 v243, v243
	v_mfma_f32_16x16x32_bf16 v[182:185], v[140:143], v[28:31], v[182:185]
	v_exp_f32_e32 v244, v244
	v_exp_f32_e32 v245, v245
	v_mfma_f32_16x16x32_bf16 v[186:189], v[144:147], v[24:27], v[222:225]
	v_exp_f32_e32 v246, v246
	v_exp_f32_e32 v247, v247
	v_mfma_f32_16x16x32_bf16 v[186:189], v[132:135], v[28:31], v[186:189]
	v_cvt_pk_bf16_f32 v248, v240, v241
	v_cvt_pk_bf16_f32 v249, v242, v243
	v_cvt_pk_bf16_f32 v250, v244, v245
	v_cvt_pk_bf16_f32 v251, v246, v247
	v_add_f32_e32 v205, v241, v240
	v_add_f32_e32 v205, v242, v205
	v_add_f32_e32 v205, v243, v205
	v_add_f32_e32 v205, v244, v205
	v_add_f32_e32 v205, v245, v205
	v_add_f32_e32 v205, v246, v205
	v_add_f32_e32 v205, v247, v205
	v_add_f32_e32 v167, v167, v205
	v_pk_fma_f32 v[240:241], v[190:191], s[34:35], v[2:3] op_sel_hi:[1,0,0] neg_lo:[0,0,1] neg_hi:[0,0,1]
	v_pk_fma_f32 v[242:243], v[192:193], s[34:35], v[2:3] op_sel_hi:[1,0,0] neg_lo:[0,0,1] neg_hi:[0,0,1]
	v_pk_fma_f32 v[244:245], v[194:195], s[34:35], v[2:3] op_sel_hi:[1,0,0] neg_lo:[0,0,1] neg_hi:[0,0,1]
	v_pk_fma_f32 v[246:247], v[196:197], s[34:35], v[2:3] op_sel_hi:[1,0,0] neg_lo:[0,0,1] neg_hi:[0,0,1]
	v_exp_f32_e32 v240, v240
	v_exp_f32_e32 v241, v241
	v_mfma_f32_16x16x32_bf16 v[190:193], v[136:139], v[32:35], v[218:221]
	v_exp_f32_e32 v242, v242
	v_exp_f32_e32 v243, v243
	v_mfma_f32_16x16x32_bf16 v[190:193], v[140:143], v[36:39], v[190:193]
	v_exp_f32_e32 v244, v244
	v_exp_f32_e32 v245, v245
	v_mfma_f32_16x16x32_bf16 v[194:197], v[144:147], v[32:35], v[222:225]
	v_exp_f32_e32 v246, v246
	v_exp_f32_e32 v247, v247
	v_mfma_f32_16x16x32_bf16 v[194:197], v[132:135], v[36:39], v[194:197]
	v_cvt_pk_bf16_f32 v198, v240, v241
	v_cvt_pk_bf16_f32 v199, v242, v243
	v_mfma_f32_16x16x32_bf16 v[104:107], v[128:131], v[248:251], v[104:107]
	v_cvt_pk_bf16_f32 v200, v244, v245
	v_cvt_pk_bf16_f32 v201, v246, v247
	v_mfma_f32_16x16x32_bf16 v[100:103], v[124:127], v[248:251], v[100:103]
	v_add_f32_e32 v205, v241, v240
	v_add_f32_e32 v205, v242, v205
	v_mfma_f32_16x16x32_bf16 v[96:99], v[120:123], v[248:251], v[96:99]
	v_add_f32_e32 v205, v243, v205
	v_add_f32_e32 v205, v244, v205
	v_mfma_f32_16x16x32_bf16 v[92:95], v[116:119], v[248:251], v[92:95]
	v_add_f32_e32 v205, v245, v205
	v_add_f32_e32 v205, v246, v205
	v_add_f32_e32 v205, v247, v205
	v_add_f32_e32 v166, v166, v205
	v_pk_fma_f32 v[240:241], v[182:183], s[34:35], v[0:1] op_sel_hi:[1,0,0] neg_lo:[0,0,1] neg_hi:[0,0,1]
	v_pk_fma_f32 v[242:243], v[184:185], s[34:35], v[0:1] op_sel_hi:[1,0,0] neg_lo:[0,0,1] neg_hi:[0,0,1]
	v_pk_fma_f32 v[244:245], v[186:187], s[34:35], v[0:1] op_sel_hi:[1,0,0] neg_lo:[0,0,1] neg_hi:[0,0,1]
	v_pk_fma_f32 v[246:247], v[188:189], s[34:35], v[0:1] op_sel_hi:[1,0,0] neg_lo:[0,0,1] neg_hi:[0,0,1]
	v_exp_f32_e32 v240, v240
	v_exp_f32_e32 v241, v241
	v_mfma_f32_16x16x32_bf16 v[88:91], v[128:131], v[198:201], v[88:91]
	v_exp_f32_e32 v242, v242
	v_exp_f32_e32 v243, v243
	v_mfma_f32_16x16x32_bf16 v[84:87], v[124:127], v[198:201], v[84:87]
	v_exp_f32_e32 v244, v244
	v_exp_f32_e32 v245, v245
	v_mfma_f32_16x16x32_bf16 v[80:83], v[120:123], v[198:201], v[80:83]
	v_exp_f32_e32 v246, v246
	v_exp_f32_e32 v247, v247
	v_mfma_f32_16x16x32_bf16 v[76:79], v[116:119], v[198:201], v[76:79]
	v_cvt_pk_bf16_f32 v248, v240, v241
	v_cvt_pk_bf16_f32 v249, v242, v243
	v_cvt_pk_bf16_f32 v250, v244, v245
	v_cvt_pk_bf16_f32 v251, v246, v247
	v_add_f32_e32 v205, v241, v240
	v_add_f32_e32 v205, v242, v205
	v_add_f32_e32 v205, v243, v205
	v_add_f32_e32 v205, v244, v205
	v_add_f32_e32 v205, v245, v205
	v_add_f32_e32 v205, v246, v205
	v_add_f32_e32 v205, v247, v205
	v_add_f32_e32 v165, v165, v205
	v_pk_fma_f32 v[240:241], v[190:191], s[34:35], v[180:181] op_sel_hi:[1,0,0] neg_lo:[0,0,1] neg_hi:[0,0,1]
	v_pk_fma_f32 v[242:243], v[192:193], s[34:35], v[180:181] op_sel_hi:[1,0,0] neg_lo:[0,0,1] neg_hi:[0,0,1]
	v_pk_fma_f32 v[244:245], v[194:195], s[34:35], v[180:181] op_sel_hi:[1,0,0] neg_lo:[0,0,1] neg_hi:[0,0,1]
	v_pk_fma_f32 v[246:247], v[196:197], s[34:35], v[180:181] op_sel_hi:[1,0,0] neg_lo:[0,0,1] neg_hi:[0,0,1]
	v_exp_f32_e32 v240, v240
	v_exp_f32_e32 v241, v241
	v_mfma_f32_16x16x32_bf16 v[72:75], v[128:131], v[248:251], v[72:75]
	v_exp_f32_e32 v242, v242
	v_exp_f32_e32 v243, v243
	v_mfma_f32_16x16x32_bf16 v[68:71], v[124:127], v[248:251], v[68:71]
	v_exp_f32_e32 v244, v244
	v_exp_f32_e32 v245, v245
	v_mfma_f32_16x16x32_bf16 v[64:67], v[120:123], v[248:251], v[64:67]
	v_exp_f32_e32 v246, v246
	v_exp_f32_e32 v247, v247
	v_mfma_f32_16x16x32_bf16 v[60:63], v[116:119], v[248:251], v[60:63]
	v_cvt_pk_bf16_f32 v198, v240, v241
	v_cvt_pk_bf16_f32 v199, v242, v243
	v_cvt_pk_bf16_f32 v200, v244, v245
	v_cvt_pk_bf16_f32 v201, v246, v247
	v_add_f32_e32 v205, v241, v240
	v_add_f32_e32 v205, v242, v205
	v_add_f32_e32 v205, v243, v205
	v_add_f32_e32 v205, v244, v205
	v_add_f32_e32 v205, v245, v205
	v_add_f32_e32 v205, v246, v205
	v_add_f32_e32 v205, v247, v205
	v_add_f32_e32 v164, v164, v205
	s_nop 0
	v_mfma_f32_16x16x32_bf16 v[56:59], v[128:131], v[198:201], v[56:59]
	v_mfma_f32_16x16x32_bf16 v[52:55], v[124:127], v[198:201], v[52:55]
	v_mfma_f32_16x16x32_bf16 v[48:51], v[120:123], v[198:201], v[48:51]
	v_mfma_f32_16x16x32_bf16 v[44:47], v[116:119], v[198:201], v[44:47]
	s_branch .LBB0_737
; #define MFMA16(a, b, c) __builtin_amdgcn_mfma_f32_16x16x32_bf16((a), (b), (c), 0, 0, 0)
; DI unsigned pk2(float lo, float hi) { f32x2 v = {lo, hi}; bf16x2_t b = __builtin_convertvector(v, bf16x2_t); return __builtin_bit_cast(unsigned, b); }
; template <int MODE>
; DI void nsa_chunk(const KVFrag& f, int kb, int t, bool selbit, const bf16x8 (&qf)[4][2], f32x4 (&O)[4][4], float (&m)[4], float (&l)[4], int quad, bool online) {
;     ...
;   for (int hh = 0; hh < 4; ++hh) {
;     f32x4 s[2];
; #pragma unroll
;     for (int a = 0; a < 2; ++a) { s[a] = MFMA16(f.k[a][0], qf[hh][0], ((f32x4){0.f, 0.f, 0.f, 0.f})); s[a] = MFMA16(f.k[a][1], qf[hh][1], s[a]); }
;     float mn = m[hh];
;     if (online) {
;       float cm = -1e30f;
; #pragma unroll
;       for (int idx = 0; idx < 8; ++idx) if (val[idx]) cm = fmaxf(cm, s[idx >> 2][idx & 3] * SC);
;       cm = fmaxf(cm, __shfl_xor(cm, 16)); cm = fmaxf(cm, __shfl_xor(cm, 32));
;       mn = fmaxf(mn, cm);
;       const float alpha = __builtin_amdgcn_exp2f(m[hh] - mn);
;       m[hh] = mn; l[hh] *= alpha;
; #pragma unroll
;       for (int dt = 0; dt < 4; ++dt) O[hh][dt] = O[hh][dt] * alpha;
;     }
;     float pv[8]; float ps = 0.f;
; #pragma unroll
;     for (int idx = 0; idx < 8; ++idx) { pv[idx] = val[idx] ? __builtin_amdgcn_exp2f(fmaf(s[idx >> 2][idx & 3], SC, -mn)) : 0.f; ps += pv[idx]; }
;     l[hh] += ps;
;     const bf16x8 pf = mk8((u32x4){pk2(pv[0], pv[1]), pk2(pv[2], pv[3]), pk2(pv[4], pv[5]), pk2(pv[6], pv[7])});
; #pragma unroll
;     for (int dt = 0; dt < 4; ++dt) O[hh][dt] = MFMA16(f.v[dt], pf, O[hh][dt]);
;   }
.Lmy_full_s1:
	s_waitcnt lgkmcnt(4)
	v_mfma_f32_16x16x32_bf16 v[182:185], v[136:139], v[8:11], v[218:221]
	v_mfma_f32_16x16x32_bf16 v[182:185], v[140:143], v[12:15], v[182:185]
	v_mfma_f32_16x16x32_bf16 v[186:189], v[144:147], v[8:11], v[218:221]
	v_mfma_f32_16x16x32_bf16 v[186:189], v[132:135], v[12:15], v[186:189]
	v_mfma_f32_16x16x32_bf16 v[190:193], v[136:139], v[16:19], v[218:221]
	v_mfma_f32_16x16x32_bf16 v[190:193], v[140:143], v[20:23], v[190:193]
	v_mfma_f32_16x16x32_bf16 v[194:197], v[144:147], v[16:19], v[218:221]
	v_mfma_f32_16x16x32_bf16 v[194:197], v[132:135], v[20:23], v[194:197]
	s_waitcnt lgkmcnt(0)
	s_nop 2
	v_pk_fma_f32 v[240:241], v[182:183], s[34:35], v[2:3] op_sel:[0,0,1] op_sel_hi:[1,0,1] neg_lo:[0,0,1] neg_hi:[0,0,1]
	v_pk_fma_f32 v[242:243], v[184:185], s[34:35], v[2:3] op_sel:[0,0,1] op_sel_hi:[1,0,1] neg_lo:[0,0,1] neg_hi:[0,0,1]
	v_pk_fma_f32 v[244:245], v[186:187], s[34:35], v[2:3] op_sel:[0,0,1] op_sel_hi:[1,0,1] neg_lo:[0,0,1] neg_hi:[0,0,1]
	v_pk_fma_f32 v[246:247], v[188:189], s[34:35], v[2:3] op_sel:[0,0,1] op_sel_hi:[1,0,1] neg_lo:[0,0,1] neg_hi:[0,0,1]
	v_exp_f32_e32 v240, v240
	v_exp_f32_e32 v241, v241
	v_mfma_f32_16x16x32_bf16 v[182:185], v[136:139], v[24:27], v[218:221]
	v_exp_f32_e32 v242, v242
	v_exp_f32_e32 v243, v243
	v_mfma_f32_16x16x32_bf16 v[182:185], v[140:143], v[28:31], v[182:185]
	v_exp_f32_e32 v244, v244
	v_exp_f32_e32 v245, v245
	v_mfma_f32_16x16x32_bf16 v[186:189], v[144:147], v[24:27], v[218:221]
	v_exp_f32_e32 v246, v246
	v_exp_f32_e32 v247, v247
	v_mfma_f32_16x16x32_bf16 v[186:189], v[132:135], v[28:31], v[186:189]
	v_cvt_pk_bf16_f32 v248, v240, v241
	v_cvt_pk_bf16_f32 v249, v242, v243
	v_cvt_pk_bf16_f32 v250, v244, v245
	v_cvt_pk_bf16_f32 v251, v246, v247
	v_add_f32_e32 v205, v241, v240
	v_add_f32_e32 v205, v242, v205
	v_add_f32_e32 v205, v243, v205
	v_add_f32_e32 v205, v244, v205
	v_add_f32_e32 v205, v245, v205
	v_add_f32_e32 v205, v246, v205
	v_add_f32_e32 v205, v247, v205
	v_add_f32_e32 v167, v167, v205
	v_pk_fma_f32 v[240:241], v[190:191], s[34:35], v[2:3] op_sel_hi:[1,0,0] neg_lo:[0,0,1] neg_hi:[0,0,1]
	v_pk_fma_f32 v[242:243], v[192:193], s[34:35], v[2:3] op_sel_hi:[1,0,0] neg_lo:[0,0,1] neg_hi:[0,0,1]
	v_pk_fma_f32 v[244:245], v[194:195], s[34:35], v[2:3] op_sel_hi:[1,0,0] neg_lo:[0,0,1] neg_hi:[0,0,1]
	v_pk_fma_f32 v[246:247], v[196:197], s[34:35], v[2:3] op_sel_hi:[1,0,0] neg_lo:[0,0,1] neg_hi:[0,0,1]
	v_exp_f32_e32 v240, v240
	v_exp_f32_e32 v241, v241
	v_mfma_f32_16x16x32_bf16 v[190:193], v[136:139], v[32:35], v[218:221]
	v_exp_f32_e32 v242, v242
	v_exp_f32_e32 v243, v243
	v_mfma_f32_16x16x32_bf16 v[190:193], v[140:143], v[36:39], v[190:193]
	v_exp_f32_e32 v244, v244
	v_exp_f32_e32 v245, v245
	v_mfma_f32_16x16x32_bf16 v[194:197], v[144:147], v[32:35], v[218:221]
	v_exp_f32_e32 v246, v246
	v_exp_f32_e32 v247, v247
	v_mfma_f32_16x16x32_bf16 v[194:197], v[132:135], v[36:39], v[194:197]
	v_cvt_pk_bf16_f32 v198, v240, v241
	v_cvt_pk_bf16_f32 v199, v242, v243
	v_mfma_f32_16x16x32_bf16 v[104:107], v[128:131], v[248:251], v[104:107]
	v_cvt_pk_bf16_f32 v200, v244, v245
	v_cvt_pk_bf16_f32 v201, v246, v247
	v_mfma_f32_16x16x32_bf16 v[100:103], v[124:127], v[248:251], v[100:103]
	v_add_f32_e32 v205, v241, v240
	v_add_f32_e32 v205, v242, v205
	v_mfma_f32_16x16x32_bf16 v[96:99], v[120:123], v[248:251], v[96:99]
	v_add_f32_e32 v205, v243, v205
	v_add_f32_e32 v205, v244, v205
	v_mfma_f32_16x16x32_bf16 v[92:95], v[116:119], v[248:251], v[92:95]
	v_add_f32_e32 v205, v245, v205
	v_add_f32_e32 v205, v246, v205
	v_add_f32_e32 v205, v247, v205
	v_add_f32_e32 v166, v166, v205
	v_pk_fma_f32 v[240:241], v[182:183], s[34:35], v[0:1] op_sel_hi:[1,0,0] neg_lo:[0,0,1] neg_hi:[0,0,1]
	v_pk_fma_f32 v[242:243], v[184:185], s[34:35], v[0:1] op_sel_hi:[1,0,0] neg_lo:[0,0,1] neg_hi:[0,0,1]
	v_pk_fma_f32 v[244:245], v[186:187], s[34:35], v[0:1] op_sel_hi:[1,0,0] neg_lo:[0,0,1] neg_hi:[0,0,1]
	v_pk_fma_f32 v[246:247], v[188:189], s[34:35], v[0:1] op_sel_hi:[1,0,0] neg_lo:[0,0,1] neg_hi:[0,0,1]
	v_exp_f32_e32 v240, v240
	v_exp_f32_e32 v241, v241
	v_mfma_f32_16x16x32_bf16 v[88:91], v[128:131], v[198:201], v[88:91]
	v_exp_f32_e32 v242, v242
	v_exp_f32_e32 v243, v243
	v_mfma_f32_16x16x32_bf16 v[84:87], v[124:127], v[198:201], v[84:87]
	v_exp_f32_e32 v244, v244
	v_exp_f32_e32 v245, v245
	v_mfma_f32_16x16x32_bf16 v[80:83], v[120:123], v[198:201], v[80:83]
	v_exp_f32_e32 v246, v246
	v_exp_f32_e32 v247, v247
	v_mfma_f32_16x16x32_bf16 v[76:79], v[116:119], v[198:201], v[76:79]
	v_cvt_pk_bf16_f32 v248, v240, v241
	v_cvt_pk_bf16_f32 v249, v242, v243
	v_cvt_pk_bf16_f32 v250, v244, v245
	v_cvt_pk_bf16_f32 v251, v246, v247
	v_add_f32_e32 v205, v241, v240
	v_add_f32_e32 v205, v242, v205
	v_add_f32_e32 v205, v243, v205
	v_add_f32_e32 v205, v244, v205
	v_add_f32_e32 v205, v245, v205
	v_add_f32_e32 v205, v246, v205
	v_add_f32_e32 v205, v247, v205
	v_add_f32_e32 v165, v165, v205
	v_pk_fma_f32 v[240:241], v[190:191], s[34:35], v[180:181] op_sel_hi:[1,0,0] neg_lo:[0,0,1] neg_hi:[0,0,1]
	v_pk_fma_f32 v[242:243], v[192:193], s[34:35], v[180:181] op_sel_hi:[1,0,0] neg_lo:[0,0,1] neg_hi:[0,0,1]
	v_pk_fma_f32 v[244:245], v[194:195], s[34:35], v[180:181] op_sel_hi:[1,0,0] neg_lo:[0,0,1] neg_hi:[0,0,1]
	v_pk_fma_f32 v[246:247], v[196:197], s[34:35], v[180:181] op_sel_hi:[1,0,0] neg_lo:[0,0,1] neg_hi:[0,0,1]
	v_exp_f32_e32 v240, v240
	v_exp_f32_e32 v241, v241
	v_mfma_f32_16x16x32_bf16 v[72:75], v[128:131], v[248:251], v[72:75]
	v_exp_f32_e32 v242, v242
	v_exp_f32_e32 v243, v243
	v_mfma_f32_16x16x32_bf16 v[68:71], v[124:127], v[248:251], v[68:71]
	v_exp_f32_e32 v244, v244
	v_exp_f32_e32 v245, v245
	v_mfma_f32_16x16x32_bf16 v[64:67], v[120:123], v[248:251], v[64:67]
	v_exp_f32_e32 v246, v246
	v_exp_f32_e32 v247, v247
	v_mfma_f32_16x16x32_bf16 v[60:63], v[116:119], v[248:251], v[60:63]
	v_cvt_pk_bf16_f32 v198, v240, v241
	v_cvt_pk_bf16_f32 v199, v242, v243
	v_cvt_pk_bf16_f32 v200, v244, v245
	v_cvt_pk_bf16_f32 v201, v246, v247
	v_add_f32_e32 v205, v241, v240
	v_add_f32_e32 v205, v242, v205
	v_add_f32_e32 v205, v243, v205
	v_add_f32_e32 v205, v244, v205
	v_add_f32_e32 v205, v245, v205
	v_add_f32_e32 v205, v246, v205
	v_add_f32_e32 v205, v247, v205
	v_add_f32_e32 v164, v164, v205
	s_nop 0
	v_mfma_f32_16x16x32_bf16 v[56:59], v[128:131], v[198:201], v[56:59]
	v_mfma_f32_16x16x32_bf16 v[52:55], v[124:127], v[198:201], v[52:55]
	v_mfma_f32_16x16x32_bf16 v[48:51], v[120:123], v[198:201], v[48:51]
	v_mfma_f32_16x16x32_bf16 v[44:47], v[116:119], v[198:201], v[44:47]
	s_branch .LBB0_737

; #define MFMA16(a, b, c) __builtin_amdgcn_mfma_f32_16x16x32_bf16((a), (b), (c), 0, 0, 0)
; DI unsigned pk2(float lo, float hi) { f32x2 v = {lo, hi}; bf16x2_t b = __builtin_convertvector(v, bf16x2_t); return __builtin_bit_cast(unsigned, b); }
; template <int MODE>
; DI void nsa_chunk(const KVFrag& f, int kb, int t, bool selbit, const bf16x8 (&qf)[4][2], f32x4 (&O)[4][4], float (&m)[4], float (&l)[4], int quad, bool online) {
;     ...
;   for (int hh = 0; hh < 4; ++hh) {
;     f32x4 s[2];
; #pragma unroll
;     for (int a = 0; a < 2; ++a) { s[a] = MFMA16(f.k[a][0], qf[hh][0], ((f32x4){0.f, 0.f, 0.f, 0.f})); s[a] = MFMA16(f.k[a][1], qf[hh][1], s[a]); }
;     float mn = m[hh];
;     if (online) {
;       float cm = -1e30f;
; #pragma unroll
;       for (int idx = 0; idx < 8; ++idx) if (val[idx]) cm = fmaxf(cm, s[idx >> 2][idx & 3] * SC);
;       cm = fmaxf(cm, __shfl_xor(cm, 16)); cm = fmaxf(cm, __shfl_xor(cm, 32));
;       mn = fmaxf(mn, cm);
;       const float alpha = __builtin_amdgcn_exp2f(m[hh] - mn);
;       m[hh] = mn; l[hh] *= alpha;
; #pragma unroll
;       for (int dt = 0; dt < 4; ++dt) O[hh][dt] = O[hh][dt] * alpha;
;     }
;     float pv[8]; float ps = 0.f;
; #pragma unroll
;     for (int idx = 0; idx < 8; ++idx) { pv[idx] = val[idx] ? __builtin_amdgcn_exp2f(fmaf(s[idx >> 2][idx & 3], SC, -mn)) : 0.f; ps += pv[idx]; }
;     l[hh] += ps;
;     const bf16x8 pf = mk8((u32x4){pk2(pv[0], pv[1]), pk2(pv[2], pv[3]), pk2(pv[4], pv[5]), pk2(pv[6], pv[7])});
; #pragma unroll
;     for (int dt = 0; dt < 4; ++dt) O[hh][dt] = MFMA16(f.v[dt], pf, O[hh][dt]);
;   }
.Lmy_fast_w1:
	s_waitcnt lgkmcnt(4)
	v_mfma_f32_16x16x32_bf16 v[182:185], v[132:135], v[8:11], v[218:221]
	v_mfma_f32_16x16x32_bf16 v[182:185], v[136:139], v[12:15], v[182:185]
	v_mfma_f32_16x16x32_bf16 v[186:189], v[140:143], v[8:11], v[222:225]
	v_mfma_f32_16x16x32_bf16 v[186:189], v[128:131], v[12:15], v[186:189]
	v_mfma_f32_16x16x32_bf16 v[190:193], v[132:135], v[16:19], v[218:221]
	v_mfma_f32_16x16x32_bf16 v[190:193], v[136:139], v[20:23], v[190:193]
	v_mfma_f32_16x16x32_bf16 v[194:197], v[140:143], v[16:19], v[222:225]
	v_mfma_f32_16x16x32_bf16 v[194:197], v[128:131], v[20:23], v[194:197]
	s_waitcnt lgkmcnt(0)
	s_nop 2
	v_pk_fma_f32 v[240:241], v[182:183], s[34:35], v[2:3] op_sel:[0,0,1] op_sel_hi:[1,0,1] neg_lo:[0,0,1] neg_hi:[0,0,1]
	v_pk_fma_f32 v[242:243], v[184:185], s[34:35], v[2:3] op_sel:[0,0,1] op_sel_hi:[1,0,1] neg_lo:[0,0,1] neg_hi:[0,0,1]
	v_pk_fma_f32 v[244:245], v[186:187], s[34:35], v[2:3] op_sel:[0,0,1] op_sel_hi:[1,0,1] neg_lo:[0,0,1] neg_hi:[0,0,1]
	v_pk_fma_f32 v[246:247], v[188:189], s[34:35], v[2:3] op_sel:[0,0,1] op_sel_hi:[1,0,1] neg_lo:[0,0,1] neg_hi:[0,0,1]
	v_exp_f32_e32 v240, v240
	v_exp_f32_e32 v241, v241
	v_mfma_f32_16x16x32_bf16 v[182:185], v[132:135], v[24:27], v[218:221]
	v_exp_f32_e32 v242, v242
	v_exp_f32_e32 v243, v243
	v_mfma_f32_16x16x32_bf16 v[182:185], v[136:139], v[28:31], v[182:185]
	v_exp_f32_e32 v244, v244
	v_exp_f32_e32 v245, v245
	v_mfma_f32_16x16x32_bf16 v[186:189], v[140:143], v[24:27], v[222:225]
	v_exp_f32_e32 v246, v246
	v_exp_f32_e32 v247, v247
	v_mfma_f32_16x16x32_bf16 v[186:189], v[128:131], v[28:31], v[186:189]
	v_cvt_pk_bf16_f32 v248, v240, v241
	v_cvt_pk_bf16_f32 v249, v242, v243
	v_cvt_pk_bf16_f32 v250, v244, v245
	v_cvt_pk_bf16_f32 v251, v246, v247
	v_add_f32_e32 v205, v241, v240
	v_add_f32_e32 v205, v242, v205
	v_add_f32_e32 v205, v243, v205
	v_add_f32_e32 v205, v244, v205
	v_add_f32_e32 v205, v245, v205
	v_add_f32_e32 v205, v246, v205
	v_add_f32_e32 v205, v247, v205
	v_add_f32_e32 v155, v155, v205
	v_pk_fma_f32 v[240:241], v[190:191], s[34:35], v[2:3] op_sel_hi:[1,0,0] neg_lo:[0,0,1] neg_hi:[0,0,1]
	v_pk_fma_f32 v[242:243], v[192:193], s[34:35], v[2:3] op_sel_hi:[1,0,0] neg_lo:[0,0,1] neg_hi:[0,0,1]
	v_pk_fma_f32 v[244:245], v[194:195], s[34:35], v[2:3] op_sel_hi:[1,0,0] neg_lo:[0,0,1] neg_hi:[0,0,1]
	v_pk_fma_f32 v[246:247], v[196:197], s[34:35], v[2:3] op_sel_hi:[1,0,0] neg_lo:[0,0,1] neg_hi:[0,0,1]
	v_exp_f32_e32 v240, v240
	v_exp_f32_e32 v241, v241
	v_mfma_f32_16x16x32_bf16 v[190:193], v[132:135], v[32:35], v[218:221]
	v_exp_f32_e32 v242, v242
	v_exp_f32_e32 v243, v243
	v_mfma_f32_16x16x32_bf16 v[190:193], v[136:139], v[36:39], v[190:193]
	v_exp_f32_e32 v244, v244
	v_exp_f32_e32 v245, v245
	v_mfma_f32_16x16x32_bf16 v[194:197], v[140:143], v[32:35], v[222:225]
	v_exp_f32_e32 v246, v246
	v_exp_f32_e32 v247, v247
	v_mfma_f32_16x16x32_bf16 v[194:197], v[128:131], v[36:39], v[194:197]
	v_cvt_pk_bf16_f32 v198, v240, v241
	v_cvt_pk_bf16_f32 v199, v242, v243
	v_mfma_f32_16x16x32_bf16 v[100:103], v[124:127], v[248:251], v[100:103]
	v_cvt_pk_bf16_f32 v200, v244, v245
	v_cvt_pk_bf16_f32 v201, v246, v247
	v_mfma_f32_16x16x32_bf16 v[96:99], v[120:123], v[248:251], v[96:99]
	v_add_f32_e32 v205, v241, v240
	v_add_f32_e32 v205, v242, v205
	v_mfma_f32_16x16x32_bf16 v[92:95], v[116:119], v[248:251], v[92:95]
	v_add_f32_e32 v205, v243, v205
	v_add_f32_e32 v205, v244, v205
	v_mfma_f32_16x16x32_bf16 v[88:91], v[112:115], v[248:251], v[88:91]
	v_add_f32_e32 v205, v245, v205
	v_add_f32_e32 v205, v246, v205
	v_add_f32_e32 v205, v247, v205
	v_add_f32_e32 v154, v154, v205
	v_pk_fma_f32 v[240:241], v[182:183], s[34:35], v[0:1] op_sel_hi:[1,0,0] neg_lo:[0,0,1] neg_hi:[0,0,1]
	v_pk_fma_f32 v[242:243], v[184:185], s[34:35], v[0:1] op_sel_hi:[1,0,0] neg_lo:[0,0,1] neg_hi:[0,0,1]
	v_pk_fma_f32 v[244:245], v[186:187], s[34:35], v[0:1] op_sel_hi:[1,0,0] neg_lo:[0,0,1] neg_hi:[0,0,1]
	v_pk_fma_f32 v[246:247], v[188:189], s[34:35], v[0:1] op_sel_hi:[1,0,0] neg_lo:[0,0,1] neg_hi:[0,0,1]
	v_exp_f32_e32 v240, v240
	v_exp_f32_e32 v241, v241
	v_mfma_f32_16x16x32_bf16 v[84:87], v[124:127], v[198:201], v[84:87]
	v_exp_f32_e32 v242, v242
	v_exp_f32_e32 v243, v243
	v_mfma_f32_16x16x32_bf16 v[80:83], v[120:123], v[198:201], v[80:83]
	v_exp_f32_e32 v244, v244
	v_exp_f32_e32 v245, v245
	v_mfma_f32_16x16x32_bf16 v[76:79], v[116:119], v[198:201], v[76:79]
	v_exp_f32_e32 v246, v246
	v_exp_f32_e32 v247, v247
	v_mfma_f32_16x16x32_bf16 v[72:75], v[112:115], v[198:201], v[72:75]
	v_cvt_pk_bf16_f32 v248, v240, v241
	v_cvt_pk_bf16_f32 v249, v242, v243
	v_cvt_pk_bf16_f32 v250, v244, v245
	v_cvt_pk_bf16_f32 v251, v246, v247
	v_add_f32_e32 v205, v241, v240
	v_add_f32_e32 v205, v242, v205
	v_add_f32_e32 v205, v243, v205
	v_add_f32_e32 v205, v244, v205
	v_add_f32_e32 v205, v245, v205
	v_add_f32_e32 v205, v246, v205
	v_add_f32_e32 v205, v247, v205
	v_add_f32_e32 v153, v153, v205
	v_pk_fma_f32 v[240:241], v[190:191], s[34:35], v[178:179] op_sel:[0,0,1] op_sel_hi:[1,0,1] neg_lo:[0,0,1] neg_hi:[0,0,1]
	v_pk_fma_f32 v[242:243], v[192:193], s[34:35], v[178:179] op_sel:[0,0,1] op_sel_hi:[1,0,1] neg_lo:[0,0,1] neg_hi:[0,0,1]
	v_pk_fma_f32 v[244:245], v[194:195], s[34:35], v[178:179] op_sel:[0,0,1] op_sel_hi:[1,0,1] neg_lo:[0,0,1] neg_hi:[0,0,1]
	v_pk_fma_f32 v[246:247], v[196:197], s[34:35], v[178:179] op_sel:[0,0,1] op_sel_hi:[1,0,1] neg_lo:[0,0,1] neg_hi:[0,0,1]
	v_exp_f32_e32 v240, v240
	v_exp_f32_e32 v241, v241
	v_mfma_f32_16x16x32_bf16 v[68:71], v[124:127], v[248:251], v[68:71]
	v_exp_f32_e32 v242, v242
	v_exp_f32_e32 v243, v243
	v_mfma_f32_16x16x32_bf16 v[64:67], v[120:123], v[248:251], v[64:67]
	v_exp_f32_e32 v244, v244
	v_exp_f32_e32 v245, v245
	v_mfma_f32_16x16x32_bf16 v[60:63], v[116:119], v[248:251], v[60:63]
	v_exp_f32_e32 v246, v246
	v_exp_f32_e32 v247, v247
	v_mfma_f32_16x16x32_bf16 v[56:59], v[112:115], v[248:251], v[56:59]
	v_cvt_pk_bf16_f32 v198, v240, v241
	v_cvt_pk_bf16_f32 v199, v242, v243
	v_cvt_pk_bf16_f32 v200, v244, v245
	v_cvt_pk_bf16_f32 v201, v246, v247
	v_add_f32_e32 v205, v241, v240
	v_add_f32_e32 v205, v242, v205
	v_add_f32_e32 v205, v243, v205
	v_add_f32_e32 v205, v244, v205
	v_add_f32_e32 v205, v245, v205
	v_add_f32_e32 v205, v246, v205
	v_add_f32_e32 v205, v247, v205
	v_add_f32_e32 v152, v152, v205
	s_nop 0
	v_mfma_f32_16x16x32_bf16 v[52:55], v[124:127], v[198:201], v[52:55]
	v_mfma_f32_16x16x32_bf16 v[48:51], v[120:123], v[198:201], v[48:51]
	v_mfma_f32_16x16x32_bf16 v[44:47], v[116:119], v[198:201], v[44:47]
	v_mfma_f32_16x16x32_bf16 v[40:43], v[112:115], v[198:201], v[40:43]
	s_branch .LBB0_767
; #define MFMA16(a, b, c) __builtin_amdgcn_mfma_f32_16x16x32_bf16((a), (b), (c), 0, 0, 0)
; DI unsigned pk2(float lo, float hi) { f32x2 v = {lo, hi}; bf16x2_t b = __builtin_convertvector(v, bf16x2_t); return __builtin_bit_cast(unsigned, b); }
; template <int MODE>
; DI void nsa_chunk(const KVFrag& f, int kb, int t, bool selbit, const bf16x8 (&qf)[4][2], f32x4 (&O)[4][4], float (&m)[4], float (&l)[4], int quad, bool online) {
;     ...
;   for (int hh = 0; hh < 4; ++hh) {
;     f32x4 s[2];
; #pragma unroll
;     for (int a = 0; a < 2; ++a) { s[a] = MFMA16(f.k[a][0], qf[hh][0], ((f32x4){0.f, 0.f, 0.f, 0.f})); s[a] = MFMA16(f.k[a][1], qf[hh][1], s[a]); }
;     float mn = m[hh];
;     if (online) {
;       float cm = -1e30f;
; #pragma unroll
;       for (int idx = 0; idx < 8; ++idx) if (val[idx]) cm = fmaxf(cm, s[idx >> 2][idx & 3] * SC);
;       cm = fmaxf(cm, __shfl_xor(cm, 16)); cm = fmaxf(cm, __shfl_xor(cm, 32));
;       mn = fmaxf(mn, cm);
;       const float alpha = __builtin_amdgcn_exp2f(m[hh] - mn);
;       m[hh] = mn; l[hh] *= alpha;
; #pragma unroll
;       for (int dt = 0; dt < 4; ++dt) O[hh][dt] = O[hh][dt] * alpha;
;     }
;     float pv[8]; float ps = 0.f;
; #pragma unroll
;     for (int idx = 0; idx < 8; ++idx) { pv[idx] = val[idx] ? __builtin_amdgcn_exp2f(fmaf(s[idx >> 2][idx & 3], SC, -mn)) : 0.f; ps += pv[idx]; }
;     l[hh] += ps;
;     const bf16x8 pf = mk8((u32x4){pk2(pv[0], pv[1]), pk2(pv[2], pv[3]), pk2(pv[4], pv[5]), pk2(pv[6], pv[7])});
; #pragma unroll
;     for (int dt = 0; dt < 4; ++dt) O[hh][dt] = MFMA16(f.v[dt], pf, O[hh][dt]);
;   }
.Lmy_full_w1:
	s_waitcnt lgkmcnt(4)
	v_mfma_f32_16x16x32_bf16 v[182:185], v[132:135], v[8:11], 0
	v_mfma_f32_16x16x32_bf16 v[182:185], v[136:139], v[12:15], v[182:185]
	v_mfma_f32_16x16x32_bf16 v[186:189], v[140:143], v[8:11], 0
	v_mfma_f32_16x16x32_bf16 v[186:189], v[128:131], v[12:15], v[186:189]
	v_mfma_f32_16x16x32_bf16 v[190:193], v[132:135], v[16:19], 0
	v_mfma_f32_16x16x32_bf16 v[190:193], v[136:139], v[20:23], v[190:193]
	v_mfma_f32_16x16x32_bf16 v[194:197], v[140:143], v[16:19], 0
	v_mfma_f32_16x16x32_bf16 v[194:197], v[128:131], v[20:23], v[194:197]
	s_waitcnt lgkmcnt(0)
	s_nop 2
	v_pk_fma_f32 v[240:241], v[182:183], s[34:35], v[2:3] op_sel:[0,0,1] op_sel_hi:[1,0,1] neg_lo:[0,0,1] neg_hi:[0,0,1]
	v_pk_fma_f32 v[242:243], v[184:185], s[34:35], v[2:3] op_sel:[0,0,1] op_sel_hi:[1,0,1] neg_lo:[0,0,1] neg_hi:[0,0,1]
	v_pk_fma_f32 v[244:245], v[186:187], s[34:35], v[2:3] op_sel:[0,0,1] op_sel_hi:[1,0,1] neg_lo:[0,0,1] neg_hi:[0,0,1]
	v_pk_fma_f32 v[246:247], v[188:189], s[34:35], v[2:3] op_sel:[0,0,1] op_sel_hi:[1,0,1] neg_lo:[0,0,1] neg_hi:[0,0,1]
	v_exp_f32_e32 v240, v240
	v_exp_f32_e32 v241, v241
	v_mfma_f32_16x16x32_bf16 v[182:185], v[132:135], v[24:27], 0
	v_exp_f32_e32 v242, v242
	v_exp_f32_e32 v243, v243
	v_mfma_f32_16x16x32_bf16 v[182:185], v[136:139], v[28:31], v[182:185]
	v_exp_f32_e32 v244, v244
	v_exp_f32_e32 v245, v245
	v_mfma_f32_16x16x32_bf16 v[186:189], v[140:143], v[24:27], 0
	v_exp_f32_e32 v246, v246
	v_exp_f32_e32 v247, v247
	v_mfma_f32_16x16x32_bf16 v[186:189], v[128:131], v[28:31], v[186:189]
	v_cvt_pk_bf16_f32 v248, v240, v241
	v_cvt_pk_bf16_f32 v249, v242, v243
	v_cvt_pk_bf16_f32 v250, v244, v245
	v_cvt_pk_bf16_f32 v251, v246, v247
	v_add_f32_e32 v205, v241, v240
	v_add_f32_e32 v205, v242, v205
	v_add_f32_e32 v205, v243, v205
	v_add_f32_e32 v205, v244, v205
	v_add_f32_e32 v205, v245, v205
	v_add_f32_e32 v205, v246, v205
	v_add_f32_e32 v205, v247, v205
	v_add_f32_e32 v155, v155, v205
	v_pk_fma_f32 v[240:241], v[190:191], s[34:35], v[2:3] op_sel_hi:[1,0,0] neg_lo:[0,0,1] neg_hi:[0,0,1]
	v_pk_fma_f32 v[242:243], v[192:193], s[34:35], v[2:3] op_sel_hi:[1,0,0] neg_lo:[0,0,1] neg_hi:[0,0,1]
	v_pk_fma_f32 v[244:245], v[194:195], s[34:35], v[2:3] op_sel_hi:[1,0,0] neg_lo:[0,0,1] neg_hi:[0,0,1]
	v_pk_fma_f32 v[246:247], v[196:197], s[34:35], v[2:3] op_sel_hi:[1,0,0] neg_lo:[0,0,1] neg_hi:[0,0,1]
	v_exp_f32_e32 v240, v240
	v_exp_f32_e32 v241, v241
	v_mfma_f32_16x16x32_bf16 v[190:193], v[132:135], v[32:35], 0
	v_exp_f32_e32 v242, v242
	v_exp_f32_e32 v243, v243
	v_mfma_f32_16x16x32_bf16 v[190:193], v[136:139], v[36:39], v[190:193]
	v_exp_f32_e32 v244, v244
	v_exp_f32_e32 v245, v245
	v_mfma_f32_16x16x32_bf16 v[194:197], v[140:143], v[32:35], 0
	v_exp_f32_e32 v246, v246
	v_exp_f32_e32 v247, v247
	v_mfma_f32_16x16x32_bf16 v[194:197], v[128:131], v[36:39], v[194:197]
	v_cvt_pk_bf16_f32 v198, v240, v241
	v_cvt_pk_bf16_f32 v199, v242, v243
	v_mfma_f32_16x16x32_bf16 v[100:103], v[124:127], v[248:251], v[100:103]
	v_cvt_pk_bf16_f32 v200, v244, v245
	v_cvt_pk_bf16_f32 v201, v246, v247
	v_mfma_f32_16x16x32_bf16 v[96:99], v[120:123], v[248:251], v[96:99]
	v_add_f32_e32 v205, v241, v240
	v_add_f32_e32 v205, v242, v205
	v_mfma_f32_16x16x32_bf16 v[92:95], v[116:119], v[248:251], v[92:95]
	v_add_f32_e32 v205, v243, v205
	v_add_f32_e32 v205, v244, v205
	v_mfma_f32_16x16x32_bf16 v[88:91], v[112:115], v[248:251], v[88:91]
	v_add_f32_e32 v205, v245, v205
	v_add_f32_e32 v205, v246, v205
	v_add_f32_e32 v205, v247, v205
	v_add_f32_e32 v154, v154, v205
	v_pk_fma_f32 v[240:241], v[182:183], s[34:35], v[0:1] op_sel_hi:[1,0,0] neg_lo:[0,0,1] neg_hi:[0,0,1]
	v_pk_fma_f32 v[242:243], v[184:185], s[34:35], v[0:1] op_sel_hi:[1,0,0] neg_lo:[0,0,1] neg_hi:[0,0,1]
	v_pk_fma_f32 v[244:245], v[186:187], s[34:35], v[0:1] op_sel_hi:[1,0,0] neg_lo:[0,0,1] neg_hi:[0,0,1]
	v_pk_fma_f32 v[246:247], v[188:189], s[34:35], v[0:1] op_sel_hi:[1,0,0] neg_lo:[0,0,1] neg_hi:[0,0,1]
	v_exp_f32_e32 v240, v240
	v_exp_f32_e32 v241, v241
	v_mfma_f32_16x16x32_bf16 v[84:87], v[124:127], v[198:201], v[84:87]
	v_exp_f32_e32 v242, v242
	v_exp_f32_e32 v243, v243
	v_mfma_f32_16x16x32_bf16 v[80:83], v[120:123], v[198:201], v[80:83]
	v_exp_f32_e32 v244, v244
	v_exp_f32_e32 v245, v245
	v_mfma_f32_16x16x32_bf16 v[76:79], v[116:119], v[198:201], v[76:79]
	v_exp_f32_e32 v246, v246
	v_exp_f32_e32 v247, v247
	v_mfma_f32_16x16x32_bf16 v[72:75], v[112:115], v[198:201], v[72:75]
	v_cvt_pk_bf16_f32 v248, v240, v241
	v_cvt_pk_bf16_f32 v249, v242, v243
	v_cvt_pk_bf16_f32 v250, v244, v245
	v_cvt_pk_bf16_f32 v251, v246, v247
	v_add_f32_e32 v205, v241, v240
	v_add_f32_e32 v205, v242, v205
	v_add_f32_e32 v205, v243, v205
	v_add_f32_e32 v205, v244, v205
	v_add_f32_e32 v205, v245, v205
	v_add_f32_e32 v205, v246, v205
	v_add_f32_e32 v205, v247, v205
	v_add_f32_e32 v153, v153, v205
	v_pk_fma_f32 v[240:241], v[190:191], s[34:35], v[178:179] op_sel:[0,0,1] op_sel_hi:[1,0,1] neg_lo:[0,0,1] neg_hi:[0,0,1]
	v_pk_fma_f32 v[242:243], v[192:193], s[34:35], v[178:179] op_sel:[0,0,1] op_sel_hi:[1,0,1] neg_lo:[0,0,1] neg_hi:[0,0,1]
	v_pk_fma_f32 v[244:245], v[194:195], s[34:35], v[178:179] op_sel:[0,0,1] op_sel_hi:[1,0,1] neg_lo:[0,0,1] neg_hi:[0,0,1]
	v_pk_fma_f32 v[246:247], v[196:197], s[34:35], v[178:179] op_sel:[0,0,1] op_sel_hi:[1,0,1] neg_lo:[0,0,1] neg_hi:[0,0,1]
	v_exp_f32_e32 v240, v240
	v_exp_f32_e32 v241, v241
	v_mfma_f32_16x16x32_bf16 v[68:71], v[124:127], v[248:251], v[68:71]
	v_exp_f32_e32 v242, v242
	v_exp_f32_e32 v243, v243
	v_mfma_f32_16x16x32_bf16 v[64:67], v[120:123], v[248:251], v[64:67]
	v_exp_f32_e32 v244, v244
	v_exp_f32_e32 v245, v245
	v_mfma_f32_16x16x32_bf16 v[60:63], v[116:119], v[248:251], v[60:63]
	v_exp_f32_e32 v246, v246
	v_exp_f32_e32 v247, v247
	v_mfma_f32_16x16x32_bf16 v[56:59], v[112:115], v[248:251], v[56:59]
	v_cvt_pk_bf16_f32 v198, v240, v241
	v_cvt_pk_bf16_f32 v199, v242, v243
	v_cvt_pk_bf16_f32 v200, v244, v245
	v_cvt_pk_bf16_f32 v201, v246, v247
	v_add_f32_e32 v205, v241, v240
	v_add_f32_e32 v205, v242, v205
	v_add_f32_e32 v205, v243, v205
	v_add_f32_e32 v205, v244, v205
	v_add_f32_e32 v205, v245, v205
	v_add_f32_e32 v205, v246, v205
	v_add_f32_e32 v205, v247, v205
	v_add_f32_e32 v152, v152, v205
	s_nop 0
	v_mfma_f32_16x16x32_bf16 v[52:55], v[124:127], v[198:201], v[52:55]
	v_mfma_f32_16x16x32_bf16 v[48:51], v[120:123], v[198:201], v[48:51]
	v_mfma_f32_16x16x32_bf16 v[44:47], v[116:119], v[198:201], v[44:47]
	v_mfma_f32_16x16x32_bf16 v[40:43], v[112:115], v[198:201], v[40:43]
	s_branch .LBB0_767
